# pool branch item rewritten: window sums by masked in-place doubling on unpacked channel pairs (same loads, exact 1/cnt and IEEE-divide silu)
# baseline (speedup 1.0000x reference)
.LBB0_298:
	v_readfirstlane_b32 s0, v226
	s_lshr_b32 s0, s0, 6
	s_lshl_b32 s0, s0, 3
	s_add_i32 s6, s54, s0
	s_add_i32 s7, s6, 15
	s_and_b32 s7, s7, 0xfff
	s_sub_i32 s8, 15, s7
	s_max_i32 s8, s8, 0
	s_mul_i32 s9, s6, 0x4200
	v_and_b32_e32 v143, 63, v226
	v_lshlrev_b32_e32 v140, 4, v143
	v_lshlrev_b32_e32 v142, 5, v143
	v_add_u32_e32 v140, s9, v140
	global_load_dwordx4 v[124:127], v142, s[58:59]
	global_load_dwordx4 v[128:131], v142, s[58:59] offset:16
	v_mov_b32_e32 v0, 0
	v_mov_b32_e32 v1, 0
	v_mov_b32_e32 v2, 0
	v_mov_b32_e32 v3, 0
	v_mov_b32_e32 v4, 0
	v_mov_b32_e32 v5, 0
	v_mov_b32_e32 v6, 0
	v_mov_b32_e32 v7, 0
	v_mov_b32_e32 v8, 0
	v_mov_b32_e32 v9, 0
	v_mov_b32_e32 v10, 0
	v_mov_b32_e32 v11, 0
	v_mov_b32_e32 v12, 0
	v_mov_b32_e32 v13, 0
	v_mov_b32_e32 v14, 0
	v_mov_b32_e32 v15, 0
	v_mov_b32_e32 v16, 0
	v_mov_b32_e32 v17, 0
	v_mov_b32_e32 v18, 0
	v_mov_b32_e32 v19, 0
	v_mov_b32_e32 v20, 0
	v_mov_b32_e32 v21, 0
	v_mov_b32_e32 v22, 0
	v_mov_b32_e32 v23, 0
	v_mov_b32_e32 v24, 0
	v_mov_b32_e32 v25, 0
	v_mov_b32_e32 v26, 0
	v_mov_b32_e32 v27, 0
	v_mov_b32_e32 v28, 0
	v_mov_b32_e32 v29, 0
	v_mov_b32_e32 v30, 0
	v_mov_b32_e32 v31, 0
	v_mov_b32_e32 v32, 0
	v_mov_b32_e32 v33, 0
	v_mov_b32_e32 v34, 0
	v_mov_b32_e32 v35, 0
	v_mov_b32_e32 v36, 0
	v_mov_b32_e32 v37, 0
	v_mov_b32_e32 v38, 0
	v_mov_b32_e32 v39, 0
	v_mov_b32_e32 v40, 0
	v_mov_b32_e32 v41, 0
	v_mov_b32_e32 v42, 0
	v_mov_b32_e32 v43, 0
	v_mov_b32_e32 v44, 0
	v_mov_b32_e32 v45, 0
	v_mov_b32_e32 v46, 0
	v_mov_b32_e32 v47, 0
	v_mov_b32_e32 v48, 0
	v_mov_b32_e32 v49, 0
	v_mov_b32_e32 v50, 0
	v_mov_b32_e32 v51, 0
	v_mov_b32_e32 v52, 0
	v_mov_b32_e32 v53, 0
	v_mov_b32_e32 v54, 0
	v_mov_b32_e32 v55, 0
	v_mov_b32_e32 v56, 0
	v_mov_b32_e32 v57, 0
	v_mov_b32_e32 v58, 0
	v_mov_b32_e32 v59, 0
	s_mov_b32 exec_lo, 0
	s_mov_b32 exec_hi, 0xffff0000
	s_cmp_le_i32 s8, 0
	s_cbranch_scc0 .Lpool_sk0
	v_mov_b32_e32 v141, v140
	global_load_dwordx4 v[0:3], v141, s[96:97]
.Lpool_sk0:
	s_cmp_le_i32 s8, 1
	s_cbranch_scc0 .Lpool_sk1
	v_add_u32_e32 v141, 0x4200, v140
	global_load_dwordx4 v[4:7], v141, s[96:97]
.Lpool_sk1:
	s_cmp_le_i32 s8, 2
	s_cbranch_scc0 .Lpool_sk2
	v_add_u32_e32 v141, 0x8400, v140
	global_load_dwordx4 v[8:11], v141, s[96:97]
.Lpool_sk2:
	s_cmp_le_i32 s8, 3
	s_cbranch_scc0 .Lpool_sk3
	v_add_u32_e32 v141, 0xc600, v140
	global_load_dwordx4 v[12:15], v141, s[96:97]
.Lpool_sk3:
	s_cmp_le_i32 s8, 4
	s_cbranch_scc0 .Lpool_sk4
	v_add_u32_e32 v141, 0x10800, v140
	global_load_dwordx4 v[16:19], v141, s[96:97]
.Lpool_sk4:
	s_cmp_le_i32 s8, 5
	s_cbranch_scc0 .Lpool_sk5
	v_add_u32_e32 v141, 0x14a00, v140
	global_load_dwordx4 v[20:23], v141, s[96:97]
.Lpool_sk5:
	s_cmp_le_i32 s8, 6
	s_cbranch_scc0 .Lpool_sk6
	v_add_u32_e32 v141, 0x18c00, v140
	global_load_dwordx4 v[24:27], v141, s[96:97]
.Lpool_sk6:
	s_cmp_le_i32 s8, 7
	s_cbranch_scc0 .Lpool_sk7
	v_add_u32_e32 v141, 0x1ce00, v140
	global_load_dwordx4 v[28:31], v141, s[96:97]
.Lpool_sk7:
	s_mov_b32 exec_lo, 0
	s_mov_b32 exec_hi, -1
	s_cmp_le_i32 s8, 8
	s_cbranch_scc0 .Lpool_sk8
	v_add_u32_e32 v141, 0x21000, v140
	global_load_dwordx4 v[32:35], v141, s[96:97]
.Lpool_sk8:
	s_cmp_le_i32 s8, 9
	s_cbranch_scc0 .Lpool_sk9
	v_add_u32_e32 v141, 0x25200, v140
	global_load_dwordx4 v[36:39], v141, s[96:97]
.Lpool_sk9:
	s_cmp_le_i32 s8, 10
	s_cbranch_scc0 .Lpool_sk10
	v_add_u32_e32 v141, 0x29400, v140
	global_load_dwordx4 v[40:43], v141, s[96:97]
.Lpool_sk10:
	s_cmp_le_i32 s8, 11
	s_cbranch_scc0 .Lpool_sk11
	v_add_u32_e32 v141, 0x2d600, v140
	global_load_dwordx4 v[44:47], v141, s[96:97]
.Lpool_sk11:
	s_mov_b32 exec_lo, 0xffff0000
	s_mov_b32 exec_hi, -1
	s_cmp_le_i32 s8, 12
	s_cbranch_scc0 .Lpool_sk12
	v_add_u32_e32 v141, 0x31800, v140
	global_load_dwordx4 v[48:51], v141, s[96:97]
.Lpool_sk12:
	s_cmp_le_i32 s8, 13
	s_cbranch_scc0 .Lpool_sk13
	v_add_u32_e32 v141, 0x35a00, v140
	global_load_dwordx4 v[52:55], v141, s[96:97]
.Lpool_sk13:
	s_mov_b32 exec_lo, -1
	s_mov_b32 exec_hi, -1
	s_cmp_le_i32 s8, 14
	s_cbranch_scc0 .Lpool_sk14
	v_add_u32_e32 v141, 0x39c00, v140
	global_load_dwordx4 v[56:59], v141, s[96:97]
.Lpool_sk14:
	v_add_u32_e32 v141, 0x3de00, v140
	global_load_dwordx4 v[60:63], v141, s[96:97]
	v_add_u32_e32 v141, 0x42000, v140
	global_load_dwordx4 v[64:67], v141, s[96:97]
	v_add_u32_e32 v141, 0x46200, v140
	global_load_dwordx4 v[68:71], v141, s[96:97]
	v_add_u32_e32 v141, 0x4a400, v140
	global_load_dwordx4 v[72:75], v141, s[96:97]
	v_add_u32_e32 v141, 0x4e600, v140
	global_load_dwordx4 v[76:79], v141, s[96:97]
	v_add_u32_e32 v141, 0x52800, v140
	global_load_dwordx4 v[80:83], v141, s[96:97]
	v_add_u32_e32 v141, 0x56a00, v140
	global_load_dwordx4 v[84:87], v141, s[96:97]
	v_add_u32_e32 v141, 0x5ac00, v140
	global_load_dwordx4 v[88:91], v141, s[96:97]
	v_add_u32_e32 v141, 0x3e200, v140
	global_load_dwordx4 v[92:95], v141, s[96:97]
	v_add_u32_e32 v141, 0x42400, v140
	global_load_dwordx4 v[96:99], v141, s[96:97]
	v_add_u32_e32 v141, 0x46600, v140
	global_load_dwordx4 v[100:103], v141, s[96:97]
	v_add_u32_e32 v141, 0x4a800, v140
	global_load_dwordx4 v[104:107], v141, s[96:97]
	v_add_u32_e32 v141, 0x4ea00, v140
	global_load_dwordx4 v[108:111], v141, s[96:97]
	v_add_u32_e32 v141, 0x52c00, v140
	global_load_dwordx4 v[112:115], v141, s[96:97]
	v_add_u32_e32 v141, 0x56e00, v140
	global_load_dwordx4 v[116:119], v141, s[96:97]
	v_add_u32_e32 v141, 0x5b000, v140
	global_load_dwordx4 v[120:123], v141, s[96:97]
	v_bfe_u32 v143, v226, 4, 2
	v_lshlrev_b32_e64 v142, v143, 2
	v_mov_b32_e32 v168, 0
	v_mov_b32_e32 v170, 0
	v_mov_b32_e32 v172, 0
	v_cmp_lt_u32_e32 vcc, 2, v142
	s_nop 1
	v_cndmask_b32_e32 v168, v168, v147, vcc
	v_cmp_lt_u32_e32 vcc, 4, v142
	s_nop 1
	v_cndmask_b32_e32 v170, v170, v147, vcc
	v_cmp_lt_u32_e32 vcc, 8, v142
	s_nop 1
	v_cndmask_b32_e32 v172, v172, v147, vcc
	s_add_i32 s0, s7, 1
	v_min_u32_e32 v132, s0, v142
	v_cvt_f32_u32_e32 v132, v132
	s_add_i32 s0, s7, 2
	v_min_u32_e32 v133, s0, v142
	v_cvt_f32_u32_e32 v133, v133
	v_div_scale_f32 v220, s[4:5], v132, v132, v147
	v_div_scale_f32 v225, s[4:5], v133, v133, v147
	v_rcp_f32_e32 v221, v220
	v_rcp_f32_e32 v144, v225
	s_nop 0
	v_fma_f32 v222, -v220, v221, 1.0
	v_fma_f32 v146, -v225, v144, 1.0
	v_fmac_f32_e32 v221, v222, v221
	v_fmac_f32_e32 v144, v146, v144
	v_div_scale_f32 v222, vcc, v147, v132, v147
	v_mul_f32_e32 v223, v222, v221
	v_fma_f32 v224, -v220, v223, v222
	v_fmac_f32_e32 v223, v224, v221
	v_fma_f32 v222, -v220, v223, v222
	s_nop 0
	v_div_fmas_f32 v222, v222, v221, v223
	v_div_scale_f32 v146, vcc, v147, v133, v147
	v_mul_f32_e32 v141, v146, v144
	v_fma_f32 v143, -v225, v141, v146
	v_fmac_f32_e32 v141, v143, v144
	v_fma_f32 v146, -v225, v141, v146
	v_div_fixup_f32 v152, v222, v132, v147
	v_div_fmas_f32 v146, v146, v144, v141
	s_nop 0
	v_div_fixup_f32 v154, v146, v133, v147
	s_add_i32 s0, s7, 3
	v_min_u32_e32 v132, s0, v142
	v_cvt_f32_u32_e32 v132, v132
	s_add_i32 s0, s7, 4
	v_min_u32_e32 v133, s0, v142
	v_cvt_f32_u32_e32 v133, v133
	v_div_scale_f32 v220, s[4:5], v132, v132, v147
	v_div_scale_f32 v225, s[4:5], v133, v133, v147
	v_rcp_f32_e32 v221, v220
	v_rcp_f32_e32 v144, v225
	s_nop 0
	v_fma_f32 v222, -v220, v221, 1.0
	v_fma_f32 v146, -v225, v144, 1.0
	v_fmac_f32_e32 v221, v222, v221
	v_fmac_f32_e32 v144, v146, v144
	v_div_scale_f32 v222, vcc, v147, v132, v147
	v_mul_f32_e32 v223, v222, v221
	v_fma_f32 v224, -v220, v223, v222
	v_fmac_f32_e32 v223, v224, v221
	v_fma_f32 v222, -v220, v223, v222
	s_nop 0
	v_div_fmas_f32 v222, v222, v221, v223
	v_div_scale_f32 v146, vcc, v147, v133, v147
	v_mul_f32_e32 v141, v146, v144
	v_fma_f32 v143, -v225, v141, v146
	v_fmac_f32_e32 v141, v143, v144
	v_fma_f32 v146, -v225, v141, v146
	v_div_fixup_f32 v156, v222, v132, v147
	v_div_fmas_f32 v146, v146, v144, v141
	s_nop 0
	v_div_fixup_f32 v158, v146, v133, v147
	s_add_i32 s0, s7, 5
	v_min_u32_e32 v132, s0, v142
	v_cvt_f32_u32_e32 v132, v132
	s_add_i32 s0, s7, 6
	v_min_u32_e32 v133, s0, v142
	v_cvt_f32_u32_e32 v133, v133
	v_div_scale_f32 v220, s[4:5], v132, v132, v147
	v_div_scale_f32 v225, s[4:5], v133, v133, v147
	v_rcp_f32_e32 v221, v220
	v_rcp_f32_e32 v144, v225
	s_nop 0
	v_fma_f32 v222, -v220, v221, 1.0
	v_fma_f32 v146, -v225, v144, 1.0
	v_fmac_f32_e32 v221, v222, v221
	v_fmac_f32_e32 v144, v146, v144
	v_div_scale_f32 v222, vcc, v147, v132, v147
	v_mul_f32_e32 v223, v222, v221
	v_fma_f32 v224, -v220, v223, v222
	v_fmac_f32_e32 v223, v224, v221
	v_fma_f32 v222, -v220, v223, v222
	s_nop 0
	v_div_fmas_f32 v222, v222, v221, v223
	v_div_scale_f32 v146, vcc, v147, v133, v147
	v_mul_f32_e32 v141, v146, v144
	v_fma_f32 v143, -v225, v141, v146
	v_fmac_f32_e32 v141, v143, v144
	v_fma_f32 v146, -v225, v141, v146
	v_div_fixup_f32 v160, v222, v132, v147
	v_div_fmas_f32 v146, v146, v144, v141
	s_nop 0
	v_div_fixup_f32 v162, v146, v133, v147
	s_add_i32 s0, s7, 7
	v_min_u32_e32 v132, s0, v142
	v_cvt_f32_u32_e32 v132, v132
	s_add_i32 s0, s7, 8
	v_min_u32_e32 v133, s0, v142
	v_cvt_f32_u32_e32 v133, v133
	v_div_scale_f32 v220, s[4:5], v132, v132, v147
	v_div_scale_f32 v225, s[4:5], v133, v133, v147
	v_rcp_f32_e32 v221, v220
	v_rcp_f32_e32 v144, v225
	s_nop 0
	v_fma_f32 v222, -v220, v221, 1.0
	v_fma_f32 v146, -v225, v144, 1.0
	v_fmac_f32_e32 v221, v222, v221
	v_fmac_f32_e32 v144, v146, v144
	v_div_scale_f32 v222, vcc, v147, v132, v147
	v_mul_f32_e32 v223, v222, v221
	v_fma_f32 v224, -v220, v223, v222
	v_fmac_f32_e32 v223, v224, v221
	v_fma_f32 v222, -v220, v223, v222
	s_nop 0
	v_div_fmas_f32 v222, v222, v221, v223
	v_div_scale_f32 v146, vcc, v147, v133, v147
	v_mul_f32_e32 v141, v146, v144
	v_fma_f32 v143, -v225, v141, v146
	v_fmac_f32_e32 v141, v143, v144
	v_fma_f32 v146, -v225, v141, v146
	v_div_fixup_f32 v164, v222, v132, v147
	v_div_fmas_f32 v146, v146, v144, v141
	s_nop 0
	v_div_fixup_f32 v166, v146, v133, v147
	s_waitcnt vmcnt(0)
	v_lshlrev_b32_e32 v174, 16, v0
	v_and_b32_e32 v175, 0xffff0000, v0
	v_lshlrev_b32_e32 v176, 16, v4
	v_and_b32_e32 v177, 0xffff0000, v4
	v_lshlrev_b32_e32 v178, 16, v8
	v_and_b32_e32 v179, 0xffff0000, v8
	v_lshlrev_b32_e32 v180, 16, v12
	v_and_b32_e32 v181, 0xffff0000, v12
	v_lshlrev_b32_e32 v182, 16, v16
	v_and_b32_e32 v183, 0xffff0000, v16
	v_lshlrev_b32_e32 v184, 16, v20
	v_and_b32_e32 v185, 0xffff0000, v20
	v_lshlrev_b32_e32 v186, 16, v24
	v_and_b32_e32 v187, 0xffff0000, v24
	v_lshlrev_b32_e32 v188, 16, v28
	v_and_b32_e32 v189, 0xffff0000, v28
	v_lshlrev_b32_e32 v190, 16, v32
	v_and_b32_e32 v191, 0xffff0000, v32
	v_lshlrev_b32_e32 v192, 16, v36
	v_and_b32_e32 v193, 0xffff0000, v36
	v_lshlrev_b32_e32 v194, 16, v40
	v_and_b32_e32 v195, 0xffff0000, v40
	v_lshlrev_b32_e32 v196, 16, v44
	v_and_b32_e32 v197, 0xffff0000, v44
	v_lshlrev_b32_e32 v198, 16, v48
	v_and_b32_e32 v199, 0xffff0000, v48
	v_lshlrev_b32_e32 v200, 16, v52
	v_and_b32_e32 v201, 0xffff0000, v52
	v_lshlrev_b32_e32 v202, 16, v56
	v_and_b32_e32 v203, 0xffff0000, v56
	v_lshlrev_b32_e32 v204, 16, v60
	v_and_b32_e32 v205, 0xffff0000, v60
	v_lshlrev_b32_e32 v206, 16, v64
	v_and_b32_e32 v207, 0xffff0000, v64
	v_lshlrev_b32_e32 v208, 16, v68
	v_and_b32_e32 v209, 0xffff0000, v68
	v_lshlrev_b32_e32 v210, 16, v72
	v_and_b32_e32 v211, 0xffff0000, v72
	v_lshlrev_b32_e32 v212, 16, v76
	v_and_b32_e32 v213, 0xffff0000, v76
	v_lshlrev_b32_e32 v214, 16, v80
	v_and_b32_e32 v215, 0xffff0000, v80
	v_lshlrev_b32_e32 v216, 16, v84
	v_and_b32_e32 v217, 0xffff0000, v84
	v_lshlrev_b32_e32 v218, 16, v88
	v_and_b32_e32 v219, 0xffff0000, v88
	v_pk_add_f32 v[218:219], v[218:219], v[216:217]
	v_pk_add_f32 v[216:217], v[216:217], v[214:215]
	v_pk_add_f32 v[214:215], v[214:215], v[212:213]
	v_pk_add_f32 v[212:213], v[212:213], v[210:211]
	v_pk_add_f32 v[210:211], v[210:211], v[208:209]
	v_pk_add_f32 v[208:209], v[208:209], v[206:207]
	v_pk_add_f32 v[206:207], v[206:207], v[204:205]
	v_pk_add_f32 v[204:205], v[204:205], v[202:203]
	v_pk_add_f32 v[202:203], v[202:203], v[200:201]
	v_pk_add_f32 v[200:201], v[200:201], v[198:199]
	v_pk_add_f32 v[198:199], v[198:199], v[196:197]
	v_pk_add_f32 v[196:197], v[196:197], v[194:195]
	v_pk_add_f32 v[194:195], v[194:195], v[192:193]
	v_pk_add_f32 v[192:193], v[192:193], v[190:191]
	v_pk_add_f32 v[190:191], v[190:191], v[188:189]
	v_pk_add_f32 v[188:189], v[188:189], v[186:187]
	v_pk_add_f32 v[186:187], v[186:187], v[184:185]
	v_pk_add_f32 v[184:185], v[184:185], v[182:183]
	v_pk_add_f32 v[182:183], v[182:183], v[180:181]
	v_pk_add_f32 v[180:181], v[180:181], v[178:179]
	v_pk_add_f32 v[178:179], v[178:179], v[176:177]
	v_pk_add_f32 v[176:177], v[176:177], v[174:175]
	v_pk_fma_f32 v[218:219], v[214:215], v[168:169], v[218:219] op_sel_hi:[1,0,1]
	v_pk_fma_f32 v[216:217], v[212:213], v[168:169], v[216:217] op_sel_hi:[1,0,1]
	v_pk_fma_f32 v[214:215], v[210:211], v[168:169], v[214:215] op_sel_hi:[1,0,1]
	v_pk_fma_f32 v[212:213], v[208:209], v[168:169], v[212:213] op_sel_hi:[1,0,1]
	v_pk_fma_f32 v[210:211], v[206:207], v[168:169], v[210:211] op_sel_hi:[1,0,1]
	v_pk_fma_f32 v[208:209], v[204:205], v[168:169], v[208:209] op_sel_hi:[1,0,1]
	v_pk_fma_f32 v[206:207], v[202:203], v[168:169], v[206:207] op_sel_hi:[1,0,1]
	v_pk_fma_f32 v[204:205], v[200:201], v[168:169], v[204:205] op_sel_hi:[1,0,1]
	v_pk_fma_f32 v[202:203], v[198:199], v[168:169], v[202:203] op_sel_hi:[1,0,1]
	v_pk_fma_f32 v[200:201], v[196:197], v[168:169], v[200:201] op_sel_hi:[1,0,1]
	v_pk_fma_f32 v[198:199], v[194:195], v[168:169], v[198:199] op_sel_hi:[1,0,1]
	v_pk_fma_f32 v[196:197], v[192:193], v[168:169], v[196:197] op_sel_hi:[1,0,1]
	v_pk_fma_f32 v[194:195], v[190:191], v[168:169], v[194:195] op_sel_hi:[1,0,1]
	v_pk_fma_f32 v[192:193], v[188:189], v[168:169], v[192:193] op_sel_hi:[1,0,1]
	v_pk_fma_f32 v[190:191], v[186:187], v[168:169], v[190:191] op_sel_hi:[1,0,1]
	v_pk_fma_f32 v[188:189], v[184:185], v[168:169], v[188:189] op_sel_hi:[1,0,1]
	v_pk_fma_f32 v[186:187], v[182:183], v[168:169], v[186:187] op_sel_hi:[1,0,1]
	v_pk_fma_f32 v[184:185], v[180:181], v[168:169], v[184:185] op_sel_hi:[1,0,1]
	v_pk_fma_f32 v[182:183], v[178:179], v[168:169], v[182:183] op_sel_hi:[1,0,1]
	v_pk_fma_f32 v[180:181], v[176:177], v[168:169], v[180:181] op_sel_hi:[1,0,1]
	v_pk_fma_f32 v[218:219], v[210:211], v[170:171], v[218:219] op_sel_hi:[1,0,1]
	v_pk_fma_f32 v[216:217], v[208:209], v[170:171], v[216:217] op_sel_hi:[1,0,1]
	v_pk_fma_f32 v[214:215], v[206:207], v[170:171], v[214:215] op_sel_hi:[1,0,1]
	v_pk_fma_f32 v[212:213], v[204:205], v[170:171], v[212:213] op_sel_hi:[1,0,1]
	v_pk_fma_f32 v[210:211], v[202:203], v[170:171], v[210:211] op_sel_hi:[1,0,1]
	v_pk_fma_f32 v[208:209], v[200:201], v[170:171], v[208:209] op_sel_hi:[1,0,1]
	v_pk_fma_f32 v[206:207], v[198:199], v[170:171], v[206:207] op_sel_hi:[1,0,1]
	v_pk_fma_f32 v[204:205], v[196:197], v[170:171], v[204:205] op_sel_hi:[1,0,1]
	v_pk_fma_f32 v[202:203], v[194:195], v[170:171], v[202:203] op_sel_hi:[1,0,1]
	v_pk_fma_f32 v[200:201], v[192:193], v[170:171], v[200:201] op_sel_hi:[1,0,1]
	v_pk_fma_f32 v[198:199], v[190:191], v[170:171], v[198:199] op_sel_hi:[1,0,1]
	v_pk_fma_f32 v[196:197], v[188:189], v[170:171], v[196:197] op_sel_hi:[1,0,1]
	v_pk_fma_f32 v[194:195], v[186:187], v[170:171], v[194:195] op_sel_hi:[1,0,1]
	v_pk_fma_f32 v[192:193], v[184:185], v[170:171], v[192:193] op_sel_hi:[1,0,1]
	v_pk_fma_f32 v[190:191], v[182:183], v[170:171], v[190:191] op_sel_hi:[1,0,1]
	v_pk_fma_f32 v[188:189], v[180:181], v[170:171], v[188:189] op_sel_hi:[1,0,1]
	v_pk_fma_f32 v[218:219], v[202:203], v[172:173], v[218:219] op_sel_hi:[1,0,1]
	v_pk_fma_f32 v[216:217], v[200:201], v[172:173], v[216:217] op_sel_hi:[1,0,1]
	v_pk_fma_f32 v[214:215], v[198:199], v[172:173], v[214:215] op_sel_hi:[1,0,1]
	v_pk_fma_f32 v[212:213], v[196:197], v[172:173], v[212:213] op_sel_hi:[1,0,1]
	v_pk_fma_f32 v[210:211], v[194:195], v[172:173], v[210:211] op_sel_hi:[1,0,1]
	v_pk_fma_f32 v[208:209], v[192:193], v[172:173], v[208:209] op_sel_hi:[1,0,1]
	v_pk_fma_f32 v[206:207], v[190:191], v[172:173], v[206:207] op_sel_hi:[1,0,1]
	v_pk_fma_f32 v[204:205], v[188:189], v[172:173], v[204:205] op_sel_hi:[1,0,1]
	v_lshlrev_b32_e32 v132, 16, v60
	v_and_b32_e32 v133, 0xffff0000, v60
	v_lshlrev_b32_e32 v134, 16, v92
	v_and_b32_e32 v135, 0xffff0000, v92
	v_mul_f32_e32 v138, 0xbfb8aa3b, v134
	v_mul_f32_e32 v139, 0xbfb8aa3b, v135
	v_exp_f32_e32 v138, v138
	v_exp_f32_e32 v139, v139
	v_pk_fma_f32 v[136:137], v[204:205], v[152:153], v[132:133] op_sel_hi:[1,0,1] neg_lo:[0,0,1] neg_hi:[0,0,1]
	v_add_f32_e32 v138, 1.0, v138
	v_add_f32_e32 v139, 1.0, v139
	v_pk_mul_f32 v[136:137], v[124:125], v[136:137]
	v_div_scale_f32 v220, s[4:5], v138, v138, v134
	v_div_scale_f32 v225, s[4:5], v139, v139, v135
	v_rcp_f32_e32 v221, v220
	v_rcp_f32_e32 v144, v225
	s_nop 0
	v_fma_f32 v222, -v220, v221, 1.0
	v_fma_f32 v146, -v225, v144, 1.0
	v_fmac_f32_e32 v221, v222, v221
	v_fmac_f32_e32 v144, v146, v144
	v_div_scale_f32 v222, vcc, v134, v138, v134
	v_mul_f32_e32 v223, v222, v221
	v_fma_f32 v224, -v220, v223, v222
	v_fmac_f32_e32 v223, v224, v221
	v_fma_f32 v222, -v220, v223, v222
	s_nop 0
	v_div_fmas_f32 v222, v222, v221, v223
	v_div_scale_f32 v146, vcc, v135, v139, v135
	v_mul_f32_e32 v141, v146, v144
	v_fma_f32 v143, -v225, v141, v146
	v_fmac_f32_e32 v141, v143, v144
	v_fma_f32 v146, -v225, v141, v146
	v_div_fixup_f32 v134, v222, v138, v134
	v_div_fmas_f32 v146, v146, v144, v141
	s_nop 0
	v_div_fixup_f32 v135, v146, v139, v135
	v_pk_mul_f32 v[136:137], v[134:135], v[136:137]
	s_nop 0
	v_cvt_pk_bf16_f32 v92, v136, v137
	v_lshlrev_b32_e32 v132, 16, v64
	v_and_b32_e32 v133, 0xffff0000, v64
	v_lshlrev_b32_e32 v134, 16, v96
	v_and_b32_e32 v135, 0xffff0000, v96
	v_mul_f32_e32 v138, 0xbfb8aa3b, v134
	v_mul_f32_e32 v139, 0xbfb8aa3b, v135
	v_exp_f32_e32 v138, v138
	v_exp_f32_e32 v139, v139
	v_pk_fma_f32 v[136:137], v[206:207], v[154:155], v[132:133] op_sel_hi:[1,0,1] neg_lo:[0,0,1] neg_hi:[0,0,1]
	v_add_f32_e32 v138, 1.0, v138
	v_add_f32_e32 v139, 1.0, v139
	v_pk_mul_f32 v[136:137], v[124:125], v[136:137]
	v_div_scale_f32 v220, s[4:5], v138, v138, v134
	v_div_scale_f32 v225, s[4:5], v139, v139, v135
	v_rcp_f32_e32 v221, v220
	v_rcp_f32_e32 v144, v225
	s_nop 0
	v_fma_f32 v222, -v220, v221, 1.0
	v_fma_f32 v146, -v225, v144, 1.0
	v_fmac_f32_e32 v221, v222, v221
	v_fmac_f32_e32 v144, v146, v144
	v_div_scale_f32 v222, vcc, v134, v138, v134
	v_mul_f32_e32 v223, v222, v221
	v_fma_f32 v224, -v220, v223, v222
	v_fmac_f32_e32 v223, v224, v221
	v_fma_f32 v222, -v220, v223, v222
	s_nop 0
	v_div_fmas_f32 v222, v222, v221, v223
	v_div_scale_f32 v146, vcc, v135, v139, v135
	v_mul_f32_e32 v141, v146, v144
	v_fma_f32 v143, -v225, v141, v146
	v_fmac_f32_e32 v141, v143, v144
	v_fma_f32 v146, -v225, v141, v146
	v_div_fixup_f32 v134, v222, v138, v134
	v_div_fmas_f32 v146, v146, v144, v141
	s_nop 0
	v_div_fixup_f32 v135, v146, v139, v135
	v_pk_mul_f32 v[136:137], v[134:135], v[136:137]
	s_nop 0
	v_cvt_pk_bf16_f32 v96, v136, v137
	v_lshlrev_b32_e32 v132, 16, v68
	v_and_b32_e32 v133, 0xffff0000, v68
	v_lshlrev_b32_e32 v134, 16, v100
	v_and_b32_e32 v135, 0xffff0000, v100
	v_mul_f32_e32 v138, 0xbfb8aa3b, v134
	v_mul_f32_e32 v139, 0xbfb8aa3b, v135
	v_exp_f32_e32 v138, v138
	v_exp_f32_e32 v139, v139
	v_pk_fma_f32 v[136:137], v[208:209], v[156:157], v[132:133] op_sel_hi:[1,0,1] neg_lo:[0,0,1] neg_hi:[0,0,1]
	v_add_f32_e32 v138, 1.0, v138
	v_add_f32_e32 v139, 1.0, v139
	v_pk_mul_f32 v[136:137], v[124:125], v[136:137]
	v_div_scale_f32 v220, s[4:5], v138, v138, v134
	v_div_scale_f32 v225, s[4:5], v139, v139, v135
	v_rcp_f32_e32 v221, v220
	v_rcp_f32_e32 v144, v225
	s_nop 0
	v_fma_f32 v222, -v220, v221, 1.0
	v_fma_f32 v146, -v225, v144, 1.0
	v_fmac_f32_e32 v221, v222, v221
	v_fmac_f32_e32 v144, v146, v144
	v_div_scale_f32 v222, vcc, v134, v138, v134
	v_mul_f32_e32 v223, v222, v221
	v_fma_f32 v224, -v220, v223, v222
	v_fmac_f32_e32 v223, v224, v221
	v_fma_f32 v222, -v220, v223, v222
	s_nop 0
	v_div_fmas_f32 v222, v222, v221, v223
	v_div_scale_f32 v146, vcc, v135, v139, v135
	v_mul_f32_e32 v141, v146, v144
	v_fma_f32 v143, -v225, v141, v146
	v_fmac_f32_e32 v141, v143, v144
	v_fma_f32 v146, -v225, v141, v146
	v_div_fixup_f32 v134, v222, v138, v134
	v_div_fmas_f32 v146, v146, v144, v141
	s_nop 0
	v_div_fixup_f32 v135, v146, v139, v135
	v_pk_mul_f32 v[136:137], v[134:135], v[136:137]
	s_nop 0
	v_cvt_pk_bf16_f32 v100, v136, v137
	v_lshlrev_b32_e32 v132, 16, v72
	v_and_b32_e32 v133, 0xffff0000, v72
	v_lshlrev_b32_e32 v134, 16, v104
	v_and_b32_e32 v135, 0xffff0000, v104
	v_mul_f32_e32 v138, 0xbfb8aa3b, v134
	v_mul_f32_e32 v139, 0xbfb8aa3b, v135
	v_exp_f32_e32 v138, v138
	v_exp_f32_e32 v139, v139
	v_pk_fma_f32 v[136:137], v[210:211], v[158:159], v[132:133] op_sel_hi:[1,0,1] neg_lo:[0,0,1] neg_hi:[0,0,1]
	v_add_f32_e32 v138, 1.0, v138
	v_add_f32_e32 v139, 1.0, v139
	v_pk_mul_f32 v[136:137], v[124:125], v[136:137]
	v_div_scale_f32 v220, s[4:5], v138, v138, v134
	v_div_scale_f32 v225, s[4:5], v139, v139, v135
	v_rcp_f32_e32 v221, v220
	v_rcp_f32_e32 v144, v225
	s_nop 0
	v_fma_f32 v222, -v220, v221, 1.0
	v_fma_f32 v146, -v225, v144, 1.0
	v_fmac_f32_e32 v221, v222, v221
	v_fmac_f32_e32 v144, v146, v144
	v_div_scale_f32 v222, vcc, v134, v138, v134
	v_mul_f32_e32 v223, v222, v221
	v_fma_f32 v224, -v220, v223, v222
	v_fmac_f32_e32 v223, v224, v221
	v_fma_f32 v222, -v220, v223, v222
	s_nop 0
	v_div_fmas_f32 v222, v222, v221, v223
	v_div_scale_f32 v146, vcc, v135, v139, v135
	v_mul_f32_e32 v141, v146, v144
	v_fma_f32 v143, -v225, v141, v146
	v_fmac_f32_e32 v141, v143, v144
	v_fma_f32 v146, -v225, v141, v146
	v_div_fixup_f32 v134, v222, v138, v134
	v_div_fmas_f32 v146, v146, v144, v141
	s_nop 0
	v_div_fixup_f32 v135, v146, v139, v135
	v_pk_mul_f32 v[136:137], v[134:135], v[136:137]
	s_nop 0
	v_cvt_pk_bf16_f32 v104, v136, v137
	v_lshlrev_b32_e32 v132, 16, v76
	v_and_b32_e32 v133, 0xffff0000, v76
	v_lshlrev_b32_e32 v134, 16, v108
	v_and_b32_e32 v135, 0xffff0000, v108
	v_mul_f32_e32 v138, 0xbfb8aa3b, v134
	v_mul_f32_e32 v139, 0xbfb8aa3b, v135
	v_exp_f32_e32 v138, v138
	v_exp_f32_e32 v139, v139
	v_pk_fma_f32 v[136:137], v[212:213], v[160:161], v[132:133] op_sel_hi:[1,0,1] neg_lo:[0,0,1] neg_hi:[0,0,1]
	v_add_f32_e32 v138, 1.0, v138
	v_add_f32_e32 v139, 1.0, v139
	v_pk_mul_f32 v[136:137], v[124:125], v[136:137]
	v_div_scale_f32 v220, s[4:5], v138, v138, v134
	v_div_scale_f32 v225, s[4:5], v139, v139, v135
	v_rcp_f32_e32 v221, v220
	v_rcp_f32_e32 v144, v225
	s_nop 0
	v_fma_f32 v222, -v220, v221, 1.0
	v_fma_f32 v146, -v225, v144, 1.0
	v_fmac_f32_e32 v221, v222, v221
	v_fmac_f32_e32 v144, v146, v144
	v_div_scale_f32 v222, vcc, v134, v138, v134
	v_mul_f32_e32 v223, v222, v221
	v_fma_f32 v224, -v220, v223, v222
	v_fmac_f32_e32 v223, v224, v221
	v_fma_f32 v222, -v220, v223, v222
	s_nop 0
	v_div_fmas_f32 v222, v222, v221, v223
	v_div_scale_f32 v146, vcc, v135, v139, v135
	v_mul_f32_e32 v141, v146, v144
	v_fma_f32 v143, -v225, v141, v146
	v_fmac_f32_e32 v141, v143, v144
	v_fma_f32 v146, -v225, v141, v146
	v_div_fixup_f32 v134, v222, v138, v134
	v_div_fmas_f32 v146, v146, v144, v141
	s_nop 0
	v_div_fixup_f32 v135, v146, v139, v135
	v_pk_mul_f32 v[136:137], v[134:135], v[136:137]
	s_nop 0
	v_cvt_pk_bf16_f32 v108, v136, v137
	v_lshlrev_b32_e32 v132, 16, v80
	v_and_b32_e32 v133, 0xffff0000, v80
	v_lshlrev_b32_e32 v134, 16, v112
	v_and_b32_e32 v135, 0xffff0000, v112
	v_mul_f32_e32 v138, 0xbfb8aa3b, v134
	v_mul_f32_e32 v139, 0xbfb8aa3b, v135
	v_exp_f32_e32 v138, v138
	v_exp_f32_e32 v139, v139
	v_pk_fma_f32 v[136:137], v[214:215], v[162:163], v[132:133] op_sel_hi:[1,0,1] neg_lo:[0,0,1] neg_hi:[0,0,1]
	v_add_f32_e32 v138, 1.0, v138
	v_add_f32_e32 v139, 1.0, v139
	v_pk_mul_f32 v[136:137], v[124:125], v[136:137]
	v_div_scale_f32 v220, s[4:5], v138, v138, v134
	v_div_scale_f32 v225, s[4:5], v139, v139, v135
	v_rcp_f32_e32 v221, v220
	v_rcp_f32_e32 v144, v225
	s_nop 0
	v_fma_f32 v222, -v220, v221, 1.0
	v_fma_f32 v146, -v225, v144, 1.0
	v_fmac_f32_e32 v221, v222, v221
	v_fmac_f32_e32 v144, v146, v144
	v_div_scale_f32 v222, vcc, v134, v138, v134
	v_mul_f32_e32 v223, v222, v221
	v_fma_f32 v224, -v220, v223, v222
	v_fmac_f32_e32 v223, v224, v221
	v_fma_f32 v222, -v220, v223, v222
	s_nop 0
	v_div_fmas_f32 v222, v222, v221, v223
	v_div_scale_f32 v146, vcc, v135, v139, v135
	v_mul_f32_e32 v141, v146, v144
	v_fma_f32 v143, -v225, v141, v146
	v_fmac_f32_e32 v141, v143, v144
	v_fma_f32 v146, -v225, v141, v146
	v_div_fixup_f32 v134, v222, v138, v134
	v_div_fmas_f32 v146, v146, v144, v141
	s_nop 0
	v_div_fixup_f32 v135, v146, v139, v135
	v_pk_mul_f32 v[136:137], v[134:135], v[136:137]
	s_nop 0
	v_cvt_pk_bf16_f32 v112, v136, v137
	v_lshlrev_b32_e32 v132, 16, v84
	v_and_b32_e32 v133, 0xffff0000, v84
	v_lshlrev_b32_e32 v134, 16, v116
	v_and_b32_e32 v135, 0xffff0000, v116
	v_mul_f32_e32 v138, 0xbfb8aa3b, v134
	v_mul_f32_e32 v139, 0xbfb8aa3b, v135
	v_exp_f32_e32 v138, v138
	v_exp_f32_e32 v139, v139
	v_pk_fma_f32 v[136:137], v[216:217], v[164:165], v[132:133] op_sel_hi:[1,0,1] neg_lo:[0,0,1] neg_hi:[0,0,1]
	v_add_f32_e32 v138, 1.0, v138
	v_add_f32_e32 v139, 1.0, v139
	v_pk_mul_f32 v[136:137], v[124:125], v[136:137]
	v_div_scale_f32 v220, s[4:5], v138, v138, v134
	v_div_scale_f32 v225, s[4:5], v139, v139, v135
	v_rcp_f32_e32 v221, v220
	v_rcp_f32_e32 v144, v225
	s_nop 0
	v_fma_f32 v222, -v220, v221, 1.0
	v_fma_f32 v146, -v225, v144, 1.0
	v_fmac_f32_e32 v221, v222, v221
	v_fmac_f32_e32 v144, v146, v144
	v_div_scale_f32 v222, vcc, v134, v138, v134
	v_mul_f32_e32 v223, v222, v221
	v_fma_f32 v224, -v220, v223, v222
	v_fmac_f32_e32 v223, v224, v221
	v_fma_f32 v222, -v220, v223, v222
	s_nop 0
	v_div_fmas_f32 v222, v222, v221, v223
	v_div_scale_f32 v146, vcc, v135, v139, v135
	v_mul_f32_e32 v141, v146, v144
	v_fma_f32 v143, -v225, v141, v146
	v_fmac_f32_e32 v141, v143, v144
	v_fma_f32 v146, -v225, v141, v146
	v_div_fixup_f32 v134, v222, v138, v134
	v_div_fmas_f32 v146, v146, v144, v141
	s_nop 0
	v_div_fixup_f32 v135, v146, v139, v135
	v_pk_mul_f32 v[136:137], v[134:135], v[136:137]
	s_nop 0
	v_cvt_pk_bf16_f32 v116, v136, v137
	v_lshlrev_b32_e32 v132, 16, v88
	v_and_b32_e32 v133, 0xffff0000, v88
	v_lshlrev_b32_e32 v134, 16, v120
	v_and_b32_e32 v135, 0xffff0000, v120
	v_mul_f32_e32 v138, 0xbfb8aa3b, v134
	v_mul_f32_e32 v139, 0xbfb8aa3b, v135
	v_exp_f32_e32 v138, v138
	v_exp_f32_e32 v139, v139
	v_pk_fma_f32 v[136:137], v[218:219], v[166:167], v[132:133] op_sel_hi:[1,0,1] neg_lo:[0,0,1] neg_hi:[0,0,1]
	v_add_f32_e32 v138, 1.0, v138
	v_add_f32_e32 v139, 1.0, v139
	v_pk_mul_f32 v[136:137], v[124:125], v[136:137]
	v_div_scale_f32 v220, s[4:5], v138, v138, v134
	v_div_scale_f32 v225, s[4:5], v139, v139, v135
	v_rcp_f32_e32 v221, v220
	v_rcp_f32_e32 v144, v225
	s_nop 0
	v_fma_f32 v222, -v220, v221, 1.0
	v_fma_f32 v146, -v225, v144, 1.0
	v_fmac_f32_e32 v221, v222, v221
	v_fmac_f32_e32 v144, v146, v144
	v_div_scale_f32 v222, vcc, v134, v138, v134
	v_mul_f32_e32 v223, v222, v221
	v_fma_f32 v224, -v220, v223, v222
	v_fmac_f32_e32 v223, v224, v221
	v_fma_f32 v222, -v220, v223, v222
	s_nop 0
	v_div_fmas_f32 v222, v222, v221, v223
	v_div_scale_f32 v146, vcc, v135, v139, v135
	v_mul_f32_e32 v141, v146, v144
	v_fma_f32 v143, -v225, v141, v146
	v_fmac_f32_e32 v141, v143, v144
	v_fma_f32 v146, -v225, v141, v146
	v_div_fixup_f32 v134, v222, v138, v134
	v_div_fmas_f32 v146, v146, v144, v141
	s_nop 0
	v_div_fixup_f32 v135, v146, v139, v135
	v_pk_mul_f32 v[136:137], v[134:135], v[136:137]
	s_nop 0
	v_cvt_pk_bf16_f32 v120, v136, v137
	v_lshlrev_b32_e32 v174, 16, v1
	v_and_b32_e32 v175, 0xffff0000, v1
	v_lshlrev_b32_e32 v176, 16, v5
	v_and_b32_e32 v177, 0xffff0000, v5
	v_lshlrev_b32_e32 v178, 16, v9
	v_and_b32_e32 v179, 0xffff0000, v9
	v_lshlrev_b32_e32 v180, 16, v13
	v_and_b32_e32 v181, 0xffff0000, v13
	v_lshlrev_b32_e32 v182, 16, v17
	v_and_b32_e32 v183, 0xffff0000, v17
	v_lshlrev_b32_e32 v184, 16, v21
	v_and_b32_e32 v185, 0xffff0000, v21
	v_lshlrev_b32_e32 v186, 16, v25
	v_and_b32_e32 v187, 0xffff0000, v25
	v_lshlrev_b32_e32 v188, 16, v29
	v_and_b32_e32 v189, 0xffff0000, v29
	v_lshlrev_b32_e32 v190, 16, v33
	v_and_b32_e32 v191, 0xffff0000, v33
	v_lshlrev_b32_e32 v192, 16, v37
	v_and_b32_e32 v193, 0xffff0000, v37
	v_lshlrev_b32_e32 v194, 16, v41
	v_and_b32_e32 v195, 0xffff0000, v41
	v_lshlrev_b32_e32 v196, 16, v45
	v_and_b32_e32 v197, 0xffff0000, v45
	v_lshlrev_b32_e32 v198, 16, v49
	v_and_b32_e32 v199, 0xffff0000, v49
	v_lshlrev_b32_e32 v200, 16, v53
	v_and_b32_e32 v201, 0xffff0000, v53
	v_lshlrev_b32_e32 v202, 16, v57
	v_and_b32_e32 v203, 0xffff0000, v57
	v_lshlrev_b32_e32 v204, 16, v61
	v_and_b32_e32 v205, 0xffff0000, v61
	v_lshlrev_b32_e32 v206, 16, v65
	v_and_b32_e32 v207, 0xffff0000, v65
	v_lshlrev_b32_e32 v208, 16, v69
	v_and_b32_e32 v209, 0xffff0000, v69
	v_lshlrev_b32_e32 v210, 16, v73
	v_and_b32_e32 v211, 0xffff0000, v73
	v_lshlrev_b32_e32 v212, 16, v77
	v_and_b32_e32 v213, 0xffff0000, v77
	v_lshlrev_b32_e32 v214, 16, v81
	v_and_b32_e32 v215, 0xffff0000, v81
	v_lshlrev_b32_e32 v216, 16, v85
	v_and_b32_e32 v217, 0xffff0000, v85
	v_lshlrev_b32_e32 v218, 16, v89
	v_and_b32_e32 v219, 0xffff0000, v89
	v_pk_add_f32 v[218:219], v[218:219], v[216:217]
	v_pk_add_f32 v[216:217], v[216:217], v[214:215]
	v_pk_add_f32 v[214:215], v[214:215], v[212:213]
	v_pk_add_f32 v[212:213], v[212:213], v[210:211]
	v_pk_add_f32 v[210:211], v[210:211], v[208:209]
	v_pk_add_f32 v[208:209], v[208:209], v[206:207]
	v_pk_add_f32 v[206:207], v[206:207], v[204:205]
	v_pk_add_f32 v[204:205], v[204:205], v[202:203]
	v_pk_add_f32 v[202:203], v[202:203], v[200:201]
	v_pk_add_f32 v[200:201], v[200:201], v[198:199]
	v_pk_add_f32 v[198:199], v[198:199], v[196:197]
	v_pk_add_f32 v[196:197], v[196:197], v[194:195]
	v_pk_add_f32 v[194:195], v[194:195], v[192:193]
	v_pk_add_f32 v[192:193], v[192:193], v[190:191]
	v_pk_add_f32 v[190:191], v[190:191], v[188:189]
	v_pk_add_f32 v[188:189], v[188:189], v[186:187]
	v_pk_add_f32 v[186:187], v[186:187], v[184:185]
	v_pk_add_f32 v[184:185], v[184:185], v[182:183]
	v_pk_add_f32 v[182:183], v[182:183], v[180:181]
	v_pk_add_f32 v[180:181], v[180:181], v[178:179]
	v_pk_add_f32 v[178:179], v[178:179], v[176:177]
	v_pk_add_f32 v[176:177], v[176:177], v[174:175]
	v_pk_fma_f32 v[218:219], v[214:215], v[168:169], v[218:219] op_sel_hi:[1,0,1]
	v_pk_fma_f32 v[216:217], v[212:213], v[168:169], v[216:217] op_sel_hi:[1,0,1]
	v_pk_fma_f32 v[214:215], v[210:211], v[168:169], v[214:215] op_sel_hi:[1,0,1]
	v_pk_fma_f32 v[212:213], v[208:209], v[168:169], v[212:213] op_sel_hi:[1,0,1]
	v_pk_fma_f32 v[210:211], v[206:207], v[168:169], v[210:211] op_sel_hi:[1,0,1]
	v_pk_fma_f32 v[208:209], v[204:205], v[168:169], v[208:209] op_sel_hi:[1,0,1]
	v_pk_fma_f32 v[206:207], v[202:203], v[168:169], v[206:207] op_sel_hi:[1,0,1]
	v_pk_fma_f32 v[204:205], v[200:201], v[168:169], v[204:205] op_sel_hi:[1,0,1]
	v_pk_fma_f32 v[202:203], v[198:199], v[168:169], v[202:203] op_sel_hi:[1,0,1]
	v_pk_fma_f32 v[200:201], v[196:197], v[168:169], v[200:201] op_sel_hi:[1,0,1]
	v_pk_fma_f32 v[198:199], v[194:195], v[168:169], v[198:199] op_sel_hi:[1,0,1]
	v_pk_fma_f32 v[196:197], v[192:193], v[168:169], v[196:197] op_sel_hi:[1,0,1]
	v_pk_fma_f32 v[194:195], v[190:191], v[168:169], v[194:195] op_sel_hi:[1,0,1]
	v_pk_fma_f32 v[192:193], v[188:189], v[168:169], v[192:193] op_sel_hi:[1,0,1]
	v_pk_fma_f32 v[190:191], v[186:187], v[168:169], v[190:191] op_sel_hi:[1,0,1]
	v_pk_fma_f32 v[188:189], v[184:185], v[168:169], v[188:189] op_sel_hi:[1,0,1]
	v_pk_fma_f32 v[186:187], v[182:183], v[168:169], v[186:187] op_sel_hi:[1,0,1]
	v_pk_fma_f32 v[184:185], v[180:181], v[168:169], v[184:185] op_sel_hi:[1,0,1]
	v_pk_fma_f32 v[182:183], v[178:179], v[168:169], v[182:183] op_sel_hi:[1,0,1]
	v_pk_fma_f32 v[180:181], v[176:177], v[168:169], v[180:181] op_sel_hi:[1,0,1]
	v_pk_fma_f32 v[218:219], v[210:211], v[170:171], v[218:219] op_sel_hi:[1,0,1]
	v_pk_fma_f32 v[216:217], v[208:209], v[170:171], v[216:217] op_sel_hi:[1,0,1]
	v_pk_fma_f32 v[214:215], v[206:207], v[170:171], v[214:215] op_sel_hi:[1,0,1]
	v_pk_fma_f32 v[212:213], v[204:205], v[170:171], v[212:213] op_sel_hi:[1,0,1]
	v_pk_fma_f32 v[210:211], v[202:203], v[170:171], v[210:211] op_sel_hi:[1,0,1]
	v_pk_fma_f32 v[208:209], v[200:201], v[170:171], v[208:209] op_sel_hi:[1,0,1]
	v_pk_fma_f32 v[206:207], v[198:199], v[170:171], v[206:207] op_sel_hi:[1,0,1]
	v_pk_fma_f32 v[204:205], v[196:197], v[170:171], v[204:205] op_sel_hi:[1,0,1]
	v_pk_fma_f32 v[202:203], v[194:195], v[170:171], v[202:203] op_sel_hi:[1,0,1]
	v_pk_fma_f32 v[200:201], v[192:193], v[170:171], v[200:201] op_sel_hi:[1,0,1]
	v_pk_fma_f32 v[198:199], v[190:191], v[170:171], v[198:199] op_sel_hi:[1,0,1]
	v_pk_fma_f32 v[196:197], v[188:189], v[170:171], v[196:197] op_sel_hi:[1,0,1]
	v_pk_fma_f32 v[194:195], v[186:187], v[170:171], v[194:195] op_sel_hi:[1,0,1]
	v_pk_fma_f32 v[192:193], v[184:185], v[170:171], v[192:193] op_sel_hi:[1,0,1]
	v_pk_fma_f32 v[190:191], v[182:183], v[170:171], v[190:191] op_sel_hi:[1,0,1]
	v_pk_fma_f32 v[188:189], v[180:181], v[170:171], v[188:189] op_sel_hi:[1,0,1]
	v_pk_fma_f32 v[218:219], v[202:203], v[172:173], v[218:219] op_sel_hi:[1,0,1]
	v_pk_fma_f32 v[216:217], v[200:201], v[172:173], v[216:217] op_sel_hi:[1,0,1]
	v_pk_fma_f32 v[214:215], v[198:199], v[172:173], v[214:215] op_sel_hi:[1,0,1]
	v_pk_fma_f32 v[212:213], v[196:197], v[172:173], v[212:213] op_sel_hi:[1,0,1]
	v_pk_fma_f32 v[210:211], v[194:195], v[172:173], v[210:211] op_sel_hi:[1,0,1]
	v_pk_fma_f32 v[208:209], v[192:193], v[172:173], v[208:209] op_sel_hi:[1,0,1]
	v_pk_fma_f32 v[206:207], v[190:191], v[172:173], v[206:207] op_sel_hi:[1,0,1]
	v_pk_fma_f32 v[204:205], v[188:189], v[172:173], v[204:205] op_sel_hi:[1,0,1]
	v_lshlrev_b32_e32 v132, 16, v61
	v_and_b32_e32 v133, 0xffff0000, v61
	v_lshlrev_b32_e32 v134, 16, v93
	v_and_b32_e32 v135, 0xffff0000, v93
	v_mul_f32_e32 v138, 0xbfb8aa3b, v134
	v_mul_f32_e32 v139, 0xbfb8aa3b, v135
	v_exp_f32_e32 v138, v138
	v_exp_f32_e32 v139, v139
	v_pk_fma_f32 v[136:137], v[204:205], v[152:153], v[132:133] op_sel_hi:[1,0,1] neg_lo:[0,0,1] neg_hi:[0,0,1]
	v_add_f32_e32 v138, 1.0, v138
	v_add_f32_e32 v139, 1.0, v139
	v_pk_mul_f32 v[136:137], v[126:127], v[136:137]
	v_div_scale_f32 v220, s[4:5], v138, v138, v134
	v_div_scale_f32 v225, s[4:5], v139, v139, v135
	v_rcp_f32_e32 v221, v220
	v_rcp_f32_e32 v144, v225
	s_nop 0
	v_fma_f32 v222, -v220, v221, 1.0
	v_fma_f32 v146, -v225, v144, 1.0
	v_fmac_f32_e32 v221, v222, v221
	v_fmac_f32_e32 v144, v146, v144
	v_div_scale_f32 v222, vcc, v134, v138, v134
	v_mul_f32_e32 v223, v222, v221
	v_fma_f32 v224, -v220, v223, v222
	v_fmac_f32_e32 v223, v224, v221
	v_fma_f32 v222, -v220, v223, v222
	s_nop 0
	v_div_fmas_f32 v222, v222, v221, v223
	v_div_scale_f32 v146, vcc, v135, v139, v135
	v_mul_f32_e32 v141, v146, v144
	v_fma_f32 v143, -v225, v141, v146
	v_fmac_f32_e32 v141, v143, v144
	v_fma_f32 v146, -v225, v141, v146
	v_div_fixup_f32 v134, v222, v138, v134
	v_div_fmas_f32 v146, v146, v144, v141
	s_nop 0
	v_div_fixup_f32 v135, v146, v139, v135
	v_pk_mul_f32 v[136:137], v[134:135], v[136:137]
	s_nop 0
	v_cvt_pk_bf16_f32 v93, v136, v137
	v_lshlrev_b32_e32 v132, 16, v65
	v_and_b32_e32 v133, 0xffff0000, v65
	v_lshlrev_b32_e32 v134, 16, v97
	v_and_b32_e32 v135, 0xffff0000, v97
	v_mul_f32_e32 v138, 0xbfb8aa3b, v134
	v_mul_f32_e32 v139, 0xbfb8aa3b, v135
	v_exp_f32_e32 v138, v138
	v_exp_f32_e32 v139, v139
	v_pk_fma_f32 v[136:137], v[206:207], v[154:155], v[132:133] op_sel_hi:[1,0,1] neg_lo:[0,0,1] neg_hi:[0,0,1]
	v_add_f32_e32 v138, 1.0, v138
	v_add_f32_e32 v139, 1.0, v139
	v_pk_mul_f32 v[136:137], v[126:127], v[136:137]
	v_div_scale_f32 v220, s[4:5], v138, v138, v134
	v_div_scale_f32 v225, s[4:5], v139, v139, v135
	v_rcp_f32_e32 v221, v220
	v_rcp_f32_e32 v144, v225
	s_nop 0
	v_fma_f32 v222, -v220, v221, 1.0
	v_fma_f32 v146, -v225, v144, 1.0
	v_fmac_f32_e32 v221, v222, v221
	v_fmac_f32_e32 v144, v146, v144
	v_div_scale_f32 v222, vcc, v134, v138, v134
	v_mul_f32_e32 v223, v222, v221
	v_fma_f32 v224, -v220, v223, v222
	v_fmac_f32_e32 v223, v224, v221
	v_fma_f32 v222, -v220, v223, v222
	s_nop 0
	v_div_fmas_f32 v222, v222, v221, v223
	v_div_scale_f32 v146, vcc, v135, v139, v135
	v_mul_f32_e32 v141, v146, v144
	v_fma_f32 v143, -v225, v141, v146
	v_fmac_f32_e32 v141, v143, v144
	v_fma_f32 v146, -v225, v141, v146
	v_div_fixup_f32 v134, v222, v138, v134
	v_div_fmas_f32 v146, v146, v144, v141
	s_nop 0
	v_div_fixup_f32 v135, v146, v139, v135
	v_pk_mul_f32 v[136:137], v[134:135], v[136:137]
	s_nop 0
	v_cvt_pk_bf16_f32 v97, v136, v137
	v_lshlrev_b32_e32 v132, 16, v69
	v_and_b32_e32 v133, 0xffff0000, v69
	v_lshlrev_b32_e32 v134, 16, v101
	v_and_b32_e32 v135, 0xffff0000, v101
	v_mul_f32_e32 v138, 0xbfb8aa3b, v134
	v_mul_f32_e32 v139, 0xbfb8aa3b, v135
	v_exp_f32_e32 v138, v138
	v_exp_f32_e32 v139, v139
	v_pk_fma_f32 v[136:137], v[208:209], v[156:157], v[132:133] op_sel_hi:[1,0,1] neg_lo:[0,0,1] neg_hi:[0,0,1]
	v_add_f32_e32 v138, 1.0, v138
	v_add_f32_e32 v139, 1.0, v139
	v_pk_mul_f32 v[136:137], v[126:127], v[136:137]
	v_div_scale_f32 v220, s[4:5], v138, v138, v134
	v_div_scale_f32 v225, s[4:5], v139, v139, v135
	v_rcp_f32_e32 v221, v220
	v_rcp_f32_e32 v144, v225
	s_nop 0
	v_fma_f32 v222, -v220, v221, 1.0
	v_fma_f32 v146, -v225, v144, 1.0
	v_fmac_f32_e32 v221, v222, v221
	v_fmac_f32_e32 v144, v146, v144
	v_div_scale_f32 v222, vcc, v134, v138, v134
	v_mul_f32_e32 v223, v222, v221
	v_fma_f32 v224, -v220, v223, v222
	v_fmac_f32_e32 v223, v224, v221
	v_fma_f32 v222, -v220, v223, v222
	s_nop 0
	v_div_fmas_f32 v222, v222, v221, v223
	v_div_scale_f32 v146, vcc, v135, v139, v135
	v_mul_f32_e32 v141, v146, v144
	v_fma_f32 v143, -v225, v141, v146
	v_fmac_f32_e32 v141, v143, v144
	v_fma_f32 v146, -v225, v141, v146
	v_div_fixup_f32 v134, v222, v138, v134
	v_div_fmas_f32 v146, v146, v144, v141
	s_nop 0
	v_div_fixup_f32 v135, v146, v139, v135
	v_pk_mul_f32 v[136:137], v[134:135], v[136:137]
	s_nop 0
	v_cvt_pk_bf16_f32 v101, v136, v137
	v_lshlrev_b32_e32 v132, 16, v73
	v_and_b32_e32 v133, 0xffff0000, v73
	v_lshlrev_b32_e32 v134, 16, v105
	v_and_b32_e32 v135, 0xffff0000, v105
	v_mul_f32_e32 v138, 0xbfb8aa3b, v134
	v_mul_f32_e32 v139, 0xbfb8aa3b, v135
	v_exp_f32_e32 v138, v138
	v_exp_f32_e32 v139, v139
	v_pk_fma_f32 v[136:137], v[210:211], v[158:159], v[132:133] op_sel_hi:[1,0,1] neg_lo:[0,0,1] neg_hi:[0,0,1]
	v_add_f32_e32 v138, 1.0, v138
	v_add_f32_e32 v139, 1.0, v139
	v_pk_mul_f32 v[136:137], v[126:127], v[136:137]
	v_div_scale_f32 v220, s[4:5], v138, v138, v134
	v_div_scale_f32 v225, s[4:5], v139, v139, v135
	v_rcp_f32_e32 v221, v220
	v_rcp_f32_e32 v144, v225
	s_nop 0
	v_fma_f32 v222, -v220, v221, 1.0
	v_fma_f32 v146, -v225, v144, 1.0
	v_fmac_f32_e32 v221, v222, v221
	v_fmac_f32_e32 v144, v146, v144
	v_div_scale_f32 v222, vcc, v134, v138, v134
	v_mul_f32_e32 v223, v222, v221
	v_fma_f32 v224, -v220, v223, v222
	v_fmac_f32_e32 v223, v224, v221
	v_fma_f32 v222, -v220, v223, v222
	s_nop 0
	v_div_fmas_f32 v222, v222, v221, v223
	v_div_scale_f32 v146, vcc, v135, v139, v135
	v_mul_f32_e32 v141, v146, v144
	v_fma_f32 v143, -v225, v141, v146
	v_fmac_f32_e32 v141, v143, v144
	v_fma_f32 v146, -v225, v141, v146
	v_div_fixup_f32 v134, v222, v138, v134
	v_div_fmas_f32 v146, v146, v144, v141
	s_nop 0
	v_div_fixup_f32 v135, v146, v139, v135
	v_pk_mul_f32 v[136:137], v[134:135], v[136:137]
	s_nop 0
	v_cvt_pk_bf16_f32 v105, v136, v137
	v_lshlrev_b32_e32 v132, 16, v77
	v_and_b32_e32 v133, 0xffff0000, v77
	v_lshlrev_b32_e32 v134, 16, v109
	v_and_b32_e32 v135, 0xffff0000, v109
	v_mul_f32_e32 v138, 0xbfb8aa3b, v134
	v_mul_f32_e32 v139, 0xbfb8aa3b, v135
	v_exp_f32_e32 v138, v138
	v_exp_f32_e32 v139, v139
	v_pk_fma_f32 v[136:137], v[212:213], v[160:161], v[132:133] op_sel_hi:[1,0,1] neg_lo:[0,0,1] neg_hi:[0,0,1]
	v_add_f32_e32 v138, 1.0, v138
	v_add_f32_e32 v139, 1.0, v139
	v_pk_mul_f32 v[136:137], v[126:127], v[136:137]
	v_div_scale_f32 v220, s[4:5], v138, v138, v134
	v_div_scale_f32 v225, s[4:5], v139, v139, v135
	v_rcp_f32_e32 v221, v220
	v_rcp_f32_e32 v144, v225
	s_nop 0
	v_fma_f32 v222, -v220, v221, 1.0
	v_fma_f32 v146, -v225, v144, 1.0
	v_fmac_f32_e32 v221, v222, v221
	v_fmac_f32_e32 v144, v146, v144
	v_div_scale_f32 v222, vcc, v134, v138, v134
	v_mul_f32_e32 v223, v222, v221
	v_fma_f32 v224, -v220, v223, v222
	v_fmac_f32_e32 v223, v224, v221
	v_fma_f32 v222, -v220, v223, v222
	s_nop 0
	v_div_fmas_f32 v222, v222, v221, v223
	v_div_scale_f32 v146, vcc, v135, v139, v135
	v_mul_f32_e32 v141, v146, v144
	v_fma_f32 v143, -v225, v141, v146
	v_fmac_f32_e32 v141, v143, v144
	v_fma_f32 v146, -v225, v141, v146
	v_div_fixup_f32 v134, v222, v138, v134
	v_div_fmas_f32 v146, v146, v144, v141
	s_nop 0
	v_div_fixup_f32 v135, v146, v139, v135
	v_pk_mul_f32 v[136:137], v[134:135], v[136:137]
	s_nop 0
	v_cvt_pk_bf16_f32 v109, v136, v137
	v_lshlrev_b32_e32 v132, 16, v81
	v_and_b32_e32 v133, 0xffff0000, v81
	v_lshlrev_b32_e32 v134, 16, v113
	v_and_b32_e32 v135, 0xffff0000, v113
	v_mul_f32_e32 v138, 0xbfb8aa3b, v134
	v_mul_f32_e32 v139, 0xbfb8aa3b, v135
	v_exp_f32_e32 v138, v138
	v_exp_f32_e32 v139, v139
	v_pk_fma_f32 v[136:137], v[214:215], v[162:163], v[132:133] op_sel_hi:[1,0,1] neg_lo:[0,0,1] neg_hi:[0,0,1]
	v_add_f32_e32 v138, 1.0, v138
	v_add_f32_e32 v139, 1.0, v139
	v_pk_mul_f32 v[136:137], v[126:127], v[136:137]
	v_div_scale_f32 v220, s[4:5], v138, v138, v134
	v_div_scale_f32 v225, s[4:5], v139, v139, v135
	v_rcp_f32_e32 v221, v220
	v_rcp_f32_e32 v144, v225
	s_nop 0
	v_fma_f32 v222, -v220, v221, 1.0
	v_fma_f32 v146, -v225, v144, 1.0
	v_fmac_f32_e32 v221, v222, v221
	v_fmac_f32_e32 v144, v146, v144
	v_div_scale_f32 v222, vcc, v134, v138, v134
	v_mul_f32_e32 v223, v222, v221
	v_fma_f32 v224, -v220, v223, v222
	v_fmac_f32_e32 v223, v224, v221
	v_fma_f32 v222, -v220, v223, v222
	s_nop 0
	v_div_fmas_f32 v222, v222, v221, v223
	v_div_scale_f32 v146, vcc, v135, v139, v135
	v_mul_f32_e32 v141, v146, v144
	v_fma_f32 v143, -v225, v141, v146
	v_fmac_f32_e32 v141, v143, v144
	v_fma_f32 v146, -v225, v141, v146
	v_div_fixup_f32 v134, v222, v138, v134
	v_div_fmas_f32 v146, v146, v144, v141
	s_nop 0
	v_div_fixup_f32 v135, v146, v139, v135
	v_pk_mul_f32 v[136:137], v[134:135], v[136:137]
	s_nop 0
	v_cvt_pk_bf16_f32 v113, v136, v137
	v_lshlrev_b32_e32 v132, 16, v85
	v_and_b32_e32 v133, 0xffff0000, v85
	v_lshlrev_b32_e32 v134, 16, v117
	v_and_b32_e32 v135, 0xffff0000, v117
	v_mul_f32_e32 v138, 0xbfb8aa3b, v134
	v_mul_f32_e32 v139, 0xbfb8aa3b, v135
	v_exp_f32_e32 v138, v138
	v_exp_f32_e32 v139, v139
	v_pk_fma_f32 v[136:137], v[216:217], v[164:165], v[132:133] op_sel_hi:[1,0,1] neg_lo:[0,0,1] neg_hi:[0,0,1]
	v_add_f32_e32 v138, 1.0, v138
	v_add_f32_e32 v139, 1.0, v139
	v_pk_mul_f32 v[136:137], v[126:127], v[136:137]
	v_div_scale_f32 v220, s[4:5], v138, v138, v134
	v_div_scale_f32 v225, s[4:5], v139, v139, v135
	v_rcp_f32_e32 v221, v220
	v_rcp_f32_e32 v144, v225
	s_nop 0
	v_fma_f32 v222, -v220, v221, 1.0
	v_fma_f32 v146, -v225, v144, 1.0
	v_fmac_f32_e32 v221, v222, v221
	v_fmac_f32_e32 v144, v146, v144
	v_div_scale_f32 v222, vcc, v134, v138, v134
	v_mul_f32_e32 v223, v222, v221
	v_fma_f32 v224, -v220, v223, v222
	v_fmac_f32_e32 v223, v224, v221
	v_fma_f32 v222, -v220, v223, v222
	s_nop 0
	v_div_fmas_f32 v222, v222, v221, v223
	v_div_scale_f32 v146, vcc, v135, v139, v135
	v_mul_f32_e32 v141, v146, v144
	v_fma_f32 v143, -v225, v141, v146
	v_fmac_f32_e32 v141, v143, v144
	v_fma_f32 v146, -v225, v141, v146
	v_div_fixup_f32 v134, v222, v138, v134
	v_div_fmas_f32 v146, v146, v144, v141
	s_nop 0
	v_div_fixup_f32 v135, v146, v139, v135
	v_pk_mul_f32 v[136:137], v[134:135], v[136:137]
	s_nop 0
	v_cvt_pk_bf16_f32 v117, v136, v137
	v_lshlrev_b32_e32 v132, 16, v89
	v_and_b32_e32 v133, 0xffff0000, v89
	v_lshlrev_b32_e32 v134, 16, v121
	v_and_b32_e32 v135, 0xffff0000, v121
	v_mul_f32_e32 v138, 0xbfb8aa3b, v134
	v_mul_f32_e32 v139, 0xbfb8aa3b, v135
	v_exp_f32_e32 v138, v138
	v_exp_f32_e32 v139, v139
	v_pk_fma_f32 v[136:137], v[218:219], v[166:167], v[132:133] op_sel_hi:[1,0,1] neg_lo:[0,0,1] neg_hi:[0,0,1]
	v_add_f32_e32 v138, 1.0, v138
	v_add_f32_e32 v139, 1.0, v139
	v_pk_mul_f32 v[136:137], v[126:127], v[136:137]
	v_div_scale_f32 v220, s[4:5], v138, v138, v134
	v_div_scale_f32 v225, s[4:5], v139, v139, v135
	v_rcp_f32_e32 v221, v220
	v_rcp_f32_e32 v144, v225
	s_nop 0
	v_fma_f32 v222, -v220, v221, 1.0
	v_fma_f32 v146, -v225, v144, 1.0
	v_fmac_f32_e32 v221, v222, v221
	v_fmac_f32_e32 v144, v146, v144
	v_div_scale_f32 v222, vcc, v134, v138, v134
	v_mul_f32_e32 v223, v222, v221
	v_fma_f32 v224, -v220, v223, v222
	v_fmac_f32_e32 v223, v224, v221
	v_fma_f32 v222, -v220, v223, v222
	s_nop 0
	v_div_fmas_f32 v222, v222, v221, v223
	v_div_scale_f32 v146, vcc, v135, v139, v135
	v_mul_f32_e32 v141, v146, v144
	v_fma_f32 v143, -v225, v141, v146
	v_fmac_f32_e32 v141, v143, v144
	v_fma_f32 v146, -v225, v141, v146
	v_div_fixup_f32 v134, v222, v138, v134
	v_div_fmas_f32 v146, v146, v144, v141
	s_nop 0
	v_div_fixup_f32 v135, v146, v139, v135
	v_pk_mul_f32 v[136:137], v[134:135], v[136:137]
	s_nop 0
	v_cvt_pk_bf16_f32 v121, v136, v137
	v_lshlrev_b32_e32 v174, 16, v2
	v_and_b32_e32 v175, 0xffff0000, v2
	v_lshlrev_b32_e32 v176, 16, v6
	v_and_b32_e32 v177, 0xffff0000, v6
	v_lshlrev_b32_e32 v178, 16, v10
	v_and_b32_e32 v179, 0xffff0000, v10
	v_lshlrev_b32_e32 v180, 16, v14
	v_and_b32_e32 v181, 0xffff0000, v14
	v_lshlrev_b32_e32 v182, 16, v18
	v_and_b32_e32 v183, 0xffff0000, v18
	v_lshlrev_b32_e32 v184, 16, v22
	v_and_b32_e32 v185, 0xffff0000, v22
	v_lshlrev_b32_e32 v186, 16, v26
	v_and_b32_e32 v187, 0xffff0000, v26
	v_lshlrev_b32_e32 v188, 16, v30
	v_and_b32_e32 v189, 0xffff0000, v30
	v_lshlrev_b32_e32 v190, 16, v34
	v_and_b32_e32 v191, 0xffff0000, v34
	v_lshlrev_b32_e32 v192, 16, v38
	v_and_b32_e32 v193, 0xffff0000, v38
	v_lshlrev_b32_e32 v194, 16, v42
	v_and_b32_e32 v195, 0xffff0000, v42
	v_lshlrev_b32_e32 v196, 16, v46
	v_and_b32_e32 v197, 0xffff0000, v46
	v_lshlrev_b32_e32 v198, 16, v50
	v_and_b32_e32 v199, 0xffff0000, v50
	v_lshlrev_b32_e32 v200, 16, v54
	v_and_b32_e32 v201, 0xffff0000, v54
	v_lshlrev_b32_e32 v202, 16, v58
	v_and_b32_e32 v203, 0xffff0000, v58
	v_lshlrev_b32_e32 v204, 16, v62
	v_and_b32_e32 v205, 0xffff0000, v62
	v_lshlrev_b32_e32 v206, 16, v66
	v_and_b32_e32 v207, 0xffff0000, v66
	v_lshlrev_b32_e32 v208, 16, v70
	v_and_b32_e32 v209, 0xffff0000, v70
	v_lshlrev_b32_e32 v210, 16, v74
	v_and_b32_e32 v211, 0xffff0000, v74
	v_lshlrev_b32_e32 v212, 16, v78
	v_and_b32_e32 v213, 0xffff0000, v78
	v_lshlrev_b32_e32 v214, 16, v82
	v_and_b32_e32 v215, 0xffff0000, v82
	v_lshlrev_b32_e32 v216, 16, v86
	v_and_b32_e32 v217, 0xffff0000, v86
	v_lshlrev_b32_e32 v218, 16, v90
	v_and_b32_e32 v219, 0xffff0000, v90
	v_pk_add_f32 v[218:219], v[218:219], v[216:217]
	v_pk_add_f32 v[216:217], v[216:217], v[214:215]
	v_pk_add_f32 v[214:215], v[214:215], v[212:213]
	v_pk_add_f32 v[212:213], v[212:213], v[210:211]
	v_pk_add_f32 v[210:211], v[210:211], v[208:209]
	v_pk_add_f32 v[208:209], v[208:209], v[206:207]
	v_pk_add_f32 v[206:207], v[206:207], v[204:205]
	v_pk_add_f32 v[204:205], v[204:205], v[202:203]
	v_pk_add_f32 v[202:203], v[202:203], v[200:201]
	v_pk_add_f32 v[200:201], v[200:201], v[198:199]
	v_pk_add_f32 v[198:199], v[198:199], v[196:197]
	v_pk_add_f32 v[196:197], v[196:197], v[194:195]
	v_pk_add_f32 v[194:195], v[194:195], v[192:193]
	v_pk_add_f32 v[192:193], v[192:193], v[190:191]
	v_pk_add_f32 v[190:191], v[190:191], v[188:189]
	v_pk_add_f32 v[188:189], v[188:189], v[186:187]
	v_pk_add_f32 v[186:187], v[186:187], v[184:185]
	v_pk_add_f32 v[184:185], v[184:185], v[182:183]
	v_pk_add_f32 v[182:183], v[182:183], v[180:181]
	v_pk_add_f32 v[180:181], v[180:181], v[178:179]
	v_pk_add_f32 v[178:179], v[178:179], v[176:177]
	v_pk_add_f32 v[176:177], v[176:177], v[174:175]
	v_pk_fma_f32 v[218:219], v[214:215], v[168:169], v[218:219] op_sel_hi:[1,0,1]
	v_pk_fma_f32 v[216:217], v[212:213], v[168:169], v[216:217] op_sel_hi:[1,0,1]
	v_pk_fma_f32 v[214:215], v[210:211], v[168:169], v[214:215] op_sel_hi:[1,0,1]
	v_pk_fma_f32 v[212:213], v[208:209], v[168:169], v[212:213] op_sel_hi:[1,0,1]
	v_pk_fma_f32 v[210:211], v[206:207], v[168:169], v[210:211] op_sel_hi:[1,0,1]
	v_pk_fma_f32 v[208:209], v[204:205], v[168:169], v[208:209] op_sel_hi:[1,0,1]
	v_pk_fma_f32 v[206:207], v[202:203], v[168:169], v[206:207] op_sel_hi:[1,0,1]
	v_pk_fma_f32 v[204:205], v[200:201], v[168:169], v[204:205] op_sel_hi:[1,0,1]
	v_pk_fma_f32 v[202:203], v[198:199], v[168:169], v[202:203] op_sel_hi:[1,0,1]
	v_pk_fma_f32 v[200:201], v[196:197], v[168:169], v[200:201] op_sel_hi:[1,0,1]
	v_pk_fma_f32 v[198:199], v[194:195], v[168:169], v[198:199] op_sel_hi:[1,0,1]
	v_pk_fma_f32 v[196:197], v[192:193], v[168:169], v[196:197] op_sel_hi:[1,0,1]
	v_pk_fma_f32 v[194:195], v[190:191], v[168:169], v[194:195] op_sel_hi:[1,0,1]
	v_pk_fma_f32 v[192:193], v[188:189], v[168:169], v[192:193] op_sel_hi:[1,0,1]
	v_pk_fma_f32 v[190:191], v[186:187], v[168:169], v[190:191] op_sel_hi:[1,0,1]
	v_pk_fma_f32 v[188:189], v[184:185], v[168:169], v[188:189] op_sel_hi:[1,0,1]
	v_pk_fma_f32 v[186:187], v[182:183], v[168:169], v[186:187] op_sel_hi:[1,0,1]
	v_pk_fma_f32 v[184:185], v[180:181], v[168:169], v[184:185] op_sel_hi:[1,0,1]
	v_pk_fma_f32 v[182:183], v[178:179], v[168:169], v[182:183] op_sel_hi:[1,0,1]
	v_pk_fma_f32 v[180:181], v[176:177], v[168:169], v[180:181] op_sel_hi:[1,0,1]
	v_pk_fma_f32 v[218:219], v[210:211], v[170:171], v[218:219] op_sel_hi:[1,0,1]
	v_pk_fma_f32 v[216:217], v[208:209], v[170:171], v[216:217] op_sel_hi:[1,0,1]
	v_pk_fma_f32 v[214:215], v[206:207], v[170:171], v[214:215] op_sel_hi:[1,0,1]
	v_pk_fma_f32 v[212:213], v[204:205], v[170:171], v[212:213] op_sel_hi:[1,0,1]
	v_pk_fma_f32 v[210:211], v[202:203], v[170:171], v[210:211] op_sel_hi:[1,0,1]
	v_pk_fma_f32 v[208:209], v[200:201], v[170:171], v[208:209] op_sel_hi:[1,0,1]
	v_pk_fma_f32 v[206:207], v[198:199], v[170:171], v[206:207] op_sel_hi:[1,0,1]
	v_pk_fma_f32 v[204:205], v[196:197], v[170:171], v[204:205] op_sel_hi:[1,0,1]
	v_pk_fma_f32 v[202:203], v[194:195], v[170:171], v[202:203] op_sel_hi:[1,0,1]
	v_pk_fma_f32 v[200:201], v[192:193], v[170:171], v[200:201] op_sel_hi:[1,0,1]
	v_pk_fma_f32 v[198:199], v[190:191], v[170:171], v[198:199] op_sel_hi:[1,0,1]
	v_pk_fma_f32 v[196:197], v[188:189], v[170:171], v[196:197] op_sel_hi:[1,0,1]
	v_pk_fma_f32 v[194:195], v[186:187], v[170:171], v[194:195] op_sel_hi:[1,0,1]
	v_pk_fma_f32 v[192:193], v[184:185], v[170:171], v[192:193] op_sel_hi:[1,0,1]
	v_pk_fma_f32 v[190:191], v[182:183], v[170:171], v[190:191] op_sel_hi:[1,0,1]
	v_pk_fma_f32 v[188:189], v[180:181], v[170:171], v[188:189] op_sel_hi:[1,0,1]
	v_pk_fma_f32 v[218:219], v[202:203], v[172:173], v[218:219] op_sel_hi:[1,0,1]
	v_pk_fma_f32 v[216:217], v[200:201], v[172:173], v[216:217] op_sel_hi:[1,0,1]
	v_pk_fma_f32 v[214:215], v[198:199], v[172:173], v[214:215] op_sel_hi:[1,0,1]
	v_pk_fma_f32 v[212:213], v[196:197], v[172:173], v[212:213] op_sel_hi:[1,0,1]
	v_pk_fma_f32 v[210:211], v[194:195], v[172:173], v[210:211] op_sel_hi:[1,0,1]
	v_pk_fma_f32 v[208:209], v[192:193], v[172:173], v[208:209] op_sel_hi:[1,0,1]
	v_pk_fma_f32 v[206:207], v[190:191], v[172:173], v[206:207] op_sel_hi:[1,0,1]
	v_pk_fma_f32 v[204:205], v[188:189], v[172:173], v[204:205] op_sel_hi:[1,0,1]
	v_lshlrev_b32_e32 v132, 16, v62
	v_and_b32_e32 v133, 0xffff0000, v62
	v_lshlrev_b32_e32 v134, 16, v94
	v_and_b32_e32 v135, 0xffff0000, v94
	v_mul_f32_e32 v138, 0xbfb8aa3b, v134
	v_mul_f32_e32 v139, 0xbfb8aa3b, v135
	v_exp_f32_e32 v138, v138
	v_exp_f32_e32 v139, v139
	v_pk_fma_f32 v[136:137], v[204:205], v[152:153], v[132:133] op_sel_hi:[1,0,1] neg_lo:[0,0,1] neg_hi:[0,0,1]
	v_add_f32_e32 v138, 1.0, v138
	v_add_f32_e32 v139, 1.0, v139
	v_pk_mul_f32 v[136:137], v[128:129], v[136:137]
	v_div_scale_f32 v220, s[4:5], v138, v138, v134
	v_div_scale_f32 v225, s[4:5], v139, v139, v135
	v_rcp_f32_e32 v221, v220
	v_rcp_f32_e32 v144, v225
	s_nop 0
	v_fma_f32 v222, -v220, v221, 1.0
	v_fma_f32 v146, -v225, v144, 1.0
	v_fmac_f32_e32 v221, v222, v221
	v_fmac_f32_e32 v144, v146, v144
	v_div_scale_f32 v222, vcc, v134, v138, v134
	v_mul_f32_e32 v223, v222, v221
	v_fma_f32 v224, -v220, v223, v222
	v_fmac_f32_e32 v223, v224, v221
	v_fma_f32 v222, -v220, v223, v222
	s_nop 0
	v_div_fmas_f32 v222, v222, v221, v223
	v_div_scale_f32 v146, vcc, v135, v139, v135
	v_mul_f32_e32 v141, v146, v144
	v_fma_f32 v143, -v225, v141, v146
	v_fmac_f32_e32 v141, v143, v144
	v_fma_f32 v146, -v225, v141, v146
	v_div_fixup_f32 v134, v222, v138, v134
	v_div_fmas_f32 v146, v146, v144, v141
	s_nop 0
	v_div_fixup_f32 v135, v146, v139, v135
	v_pk_mul_f32 v[136:137], v[134:135], v[136:137]
	s_nop 0
	v_cvt_pk_bf16_f32 v94, v136, v137
	v_lshlrev_b32_e32 v132, 16, v66
	v_and_b32_e32 v133, 0xffff0000, v66
	v_lshlrev_b32_e32 v134, 16, v98
	v_and_b32_e32 v135, 0xffff0000, v98
	v_mul_f32_e32 v138, 0xbfb8aa3b, v134
	v_mul_f32_e32 v139, 0xbfb8aa3b, v135
	v_exp_f32_e32 v138, v138
	v_exp_f32_e32 v139, v139
	v_pk_fma_f32 v[136:137], v[206:207], v[154:155], v[132:133] op_sel_hi:[1,0,1] neg_lo:[0,0,1] neg_hi:[0,0,1]
	v_add_f32_e32 v138, 1.0, v138
	v_add_f32_e32 v139, 1.0, v139
	v_pk_mul_f32 v[136:137], v[128:129], v[136:137]
	v_div_scale_f32 v220, s[4:5], v138, v138, v134
	v_div_scale_f32 v225, s[4:5], v139, v139, v135
	v_rcp_f32_e32 v221, v220
	v_rcp_f32_e32 v144, v225
	s_nop 0
	v_fma_f32 v222, -v220, v221, 1.0
	v_fma_f32 v146, -v225, v144, 1.0
	v_fmac_f32_e32 v221, v222, v221
	v_fmac_f32_e32 v144, v146, v144
	v_div_scale_f32 v222, vcc, v134, v138, v134
	v_mul_f32_e32 v223, v222, v221
	v_fma_f32 v224, -v220, v223, v222
	v_fmac_f32_e32 v223, v224, v221
	v_fma_f32 v222, -v220, v223, v222
	s_nop 0
	v_div_fmas_f32 v222, v222, v221, v223
	v_div_scale_f32 v146, vcc, v135, v139, v135
	v_mul_f32_e32 v141, v146, v144
	v_fma_f32 v143, -v225, v141, v146
	v_fmac_f32_e32 v141, v143, v144
	v_fma_f32 v146, -v225, v141, v146
	v_div_fixup_f32 v134, v222, v138, v134
	v_div_fmas_f32 v146, v146, v144, v141
	s_nop 0
	v_div_fixup_f32 v135, v146, v139, v135
	v_pk_mul_f32 v[136:137], v[134:135], v[136:137]
	s_nop 0
	v_cvt_pk_bf16_f32 v98, v136, v137
	v_lshlrev_b32_e32 v132, 16, v70
	v_and_b32_e32 v133, 0xffff0000, v70
	v_lshlrev_b32_e32 v134, 16, v102
	v_and_b32_e32 v135, 0xffff0000, v102
	v_mul_f32_e32 v138, 0xbfb8aa3b, v134
	v_mul_f32_e32 v139, 0xbfb8aa3b, v135
	v_exp_f32_e32 v138, v138
	v_exp_f32_e32 v139, v139
	v_pk_fma_f32 v[136:137], v[208:209], v[156:157], v[132:133] op_sel_hi:[1,0,1] neg_lo:[0,0,1] neg_hi:[0,0,1]
	v_add_f32_e32 v138, 1.0, v138
	v_add_f32_e32 v139, 1.0, v139
	v_pk_mul_f32 v[136:137], v[128:129], v[136:137]
	v_div_scale_f32 v220, s[4:5], v138, v138, v134
	v_div_scale_f32 v225, s[4:5], v139, v139, v135
	v_rcp_f32_e32 v221, v220
	v_rcp_f32_e32 v144, v225
	s_nop 0
	v_fma_f32 v222, -v220, v221, 1.0
	v_fma_f32 v146, -v225, v144, 1.0
	v_fmac_f32_e32 v221, v222, v221
	v_fmac_f32_e32 v144, v146, v144
	v_div_scale_f32 v222, vcc, v134, v138, v134
	v_mul_f32_e32 v223, v222, v221
	v_fma_f32 v224, -v220, v223, v222
	v_fmac_f32_e32 v223, v224, v221
	v_fma_f32 v222, -v220, v223, v222
	s_nop 0
	v_div_fmas_f32 v222, v222, v221, v223
	v_div_scale_f32 v146, vcc, v135, v139, v135
	v_mul_f32_e32 v141, v146, v144
	v_fma_f32 v143, -v225, v141, v146
	v_fmac_f32_e32 v141, v143, v144
	v_fma_f32 v146, -v225, v141, v146
	v_div_fixup_f32 v134, v222, v138, v134
	v_div_fmas_f32 v146, v146, v144, v141
	s_nop 0
	v_div_fixup_f32 v135, v146, v139, v135
	v_pk_mul_f32 v[136:137], v[134:135], v[136:137]
	s_nop 0
	v_cvt_pk_bf16_f32 v102, v136, v137
	v_lshlrev_b32_e32 v132, 16, v74
	v_and_b32_e32 v133, 0xffff0000, v74
	v_lshlrev_b32_e32 v134, 16, v106
	v_and_b32_e32 v135, 0xffff0000, v106
	v_mul_f32_e32 v138, 0xbfb8aa3b, v134
	v_mul_f32_e32 v139, 0xbfb8aa3b, v135
	v_exp_f32_e32 v138, v138
	v_exp_f32_e32 v139, v139
	v_pk_fma_f32 v[136:137], v[210:211], v[158:159], v[132:133] op_sel_hi:[1,0,1] neg_lo:[0,0,1] neg_hi:[0,0,1]
	v_add_f32_e32 v138, 1.0, v138
	v_add_f32_e32 v139, 1.0, v139
	v_pk_mul_f32 v[136:137], v[128:129], v[136:137]
	v_div_scale_f32 v220, s[4:5], v138, v138, v134
	v_div_scale_f32 v225, s[4:5], v139, v139, v135
	v_rcp_f32_e32 v221, v220
	v_rcp_f32_e32 v144, v225
	s_nop 0
	v_fma_f32 v222, -v220, v221, 1.0
	v_fma_f32 v146, -v225, v144, 1.0
	v_fmac_f32_e32 v221, v222, v221
	v_fmac_f32_e32 v144, v146, v144
	v_div_scale_f32 v222, vcc, v134, v138, v134
	v_mul_f32_e32 v223, v222, v221
	v_fma_f32 v224, -v220, v223, v222
	v_fmac_f32_e32 v223, v224, v221
	v_fma_f32 v222, -v220, v223, v222
	s_nop 0
	v_div_fmas_f32 v222, v222, v221, v223
	v_div_scale_f32 v146, vcc, v135, v139, v135
	v_mul_f32_e32 v141, v146, v144
	v_fma_f32 v143, -v225, v141, v146
	v_fmac_f32_e32 v141, v143, v144
	v_fma_f32 v146, -v225, v141, v146
	v_div_fixup_f32 v134, v222, v138, v134
	v_div_fmas_f32 v146, v146, v144, v141
	s_nop 0
	v_div_fixup_f32 v135, v146, v139, v135
	v_pk_mul_f32 v[136:137], v[134:135], v[136:137]
	s_nop 0
	v_cvt_pk_bf16_f32 v106, v136, v137
	v_lshlrev_b32_e32 v132, 16, v78
	v_and_b32_e32 v133, 0xffff0000, v78
	v_lshlrev_b32_e32 v134, 16, v110
	v_and_b32_e32 v135, 0xffff0000, v110
	v_mul_f32_e32 v138, 0xbfb8aa3b, v134
	v_mul_f32_e32 v139, 0xbfb8aa3b, v135
	v_exp_f32_e32 v138, v138
	v_exp_f32_e32 v139, v139
	v_pk_fma_f32 v[136:137], v[212:213], v[160:161], v[132:133] op_sel_hi:[1,0,1] neg_lo:[0,0,1] neg_hi:[0,0,1]
	v_add_f32_e32 v138, 1.0, v138
	v_add_f32_e32 v139, 1.0, v139
	v_pk_mul_f32 v[136:137], v[128:129], v[136:137]
	v_div_scale_f32 v220, s[4:5], v138, v138, v134
	v_div_scale_f32 v225, s[4:5], v139, v139, v135
	v_rcp_f32_e32 v221, v220
	v_rcp_f32_e32 v144, v225
	s_nop 0
	v_fma_f32 v222, -v220, v221, 1.0
	v_fma_f32 v146, -v225, v144, 1.0
	v_fmac_f32_e32 v221, v222, v221
	v_fmac_f32_e32 v144, v146, v144
	v_div_scale_f32 v222, vcc, v134, v138, v134
	v_mul_f32_e32 v223, v222, v221
	v_fma_f32 v224, -v220, v223, v222
	v_fmac_f32_e32 v223, v224, v221
	v_fma_f32 v222, -v220, v223, v222
	s_nop 0
	v_div_fmas_f32 v222, v222, v221, v223
	v_div_scale_f32 v146, vcc, v135, v139, v135
	v_mul_f32_e32 v141, v146, v144
	v_fma_f32 v143, -v225, v141, v146
	v_fmac_f32_e32 v141, v143, v144
	v_fma_f32 v146, -v225, v141, v146
	v_div_fixup_f32 v134, v222, v138, v134
	v_div_fmas_f32 v146, v146, v144, v141
	s_nop 0
	v_div_fixup_f32 v135, v146, v139, v135
	v_pk_mul_f32 v[136:137], v[134:135], v[136:137]
	s_nop 0
	v_cvt_pk_bf16_f32 v110, v136, v137
	v_lshlrev_b32_e32 v132, 16, v82
	v_and_b32_e32 v133, 0xffff0000, v82
	v_lshlrev_b32_e32 v134, 16, v114
	v_and_b32_e32 v135, 0xffff0000, v114
	v_mul_f32_e32 v138, 0xbfb8aa3b, v134
	v_mul_f32_e32 v139, 0xbfb8aa3b, v135
	v_exp_f32_e32 v138, v138
	v_exp_f32_e32 v139, v139
	v_pk_fma_f32 v[136:137], v[214:215], v[162:163], v[132:133] op_sel_hi:[1,0,1] neg_lo:[0,0,1] neg_hi:[0,0,1]
	v_add_f32_e32 v138, 1.0, v138
	v_add_f32_e32 v139, 1.0, v139
	v_pk_mul_f32 v[136:137], v[128:129], v[136:137]
	v_div_scale_f32 v220, s[4:5], v138, v138, v134
	v_div_scale_f32 v225, s[4:5], v139, v139, v135
	v_rcp_f32_e32 v221, v220
	v_rcp_f32_e32 v144, v225
	s_nop 0
	v_fma_f32 v222, -v220, v221, 1.0
	v_fma_f32 v146, -v225, v144, 1.0
	v_fmac_f32_e32 v221, v222, v221
	v_fmac_f32_e32 v144, v146, v144
	v_div_scale_f32 v222, vcc, v134, v138, v134
	v_mul_f32_e32 v223, v222, v221
	v_fma_f32 v224, -v220, v223, v222
	v_fmac_f32_e32 v223, v224, v221
	v_fma_f32 v222, -v220, v223, v222
	s_nop 0
	v_div_fmas_f32 v222, v222, v221, v223
	v_div_scale_f32 v146, vcc, v135, v139, v135
	v_mul_f32_e32 v141, v146, v144
	v_fma_f32 v143, -v225, v141, v146
	v_fmac_f32_e32 v141, v143, v144
	v_fma_f32 v146, -v225, v141, v146
	v_div_fixup_f32 v134, v222, v138, v134
	v_div_fmas_f32 v146, v146, v144, v141
	s_nop 0
	v_div_fixup_f32 v135, v146, v139, v135
	v_pk_mul_f32 v[136:137], v[134:135], v[136:137]
	s_nop 0
	v_cvt_pk_bf16_f32 v114, v136, v137
	v_lshlrev_b32_e32 v132, 16, v86
	v_and_b32_e32 v133, 0xffff0000, v86
	v_lshlrev_b32_e32 v134, 16, v118
	v_and_b32_e32 v135, 0xffff0000, v118
	v_mul_f32_e32 v138, 0xbfb8aa3b, v134
	v_mul_f32_e32 v139, 0xbfb8aa3b, v135
	v_exp_f32_e32 v138, v138
	v_exp_f32_e32 v139, v139
	v_pk_fma_f32 v[136:137], v[216:217], v[164:165], v[132:133] op_sel_hi:[1,0,1] neg_lo:[0,0,1] neg_hi:[0,0,1]
	v_add_f32_e32 v138, 1.0, v138
	v_add_f32_e32 v139, 1.0, v139
	v_pk_mul_f32 v[136:137], v[128:129], v[136:137]
	v_div_scale_f32 v220, s[4:5], v138, v138, v134
	v_div_scale_f32 v225, s[4:5], v139, v139, v135
	v_rcp_f32_e32 v221, v220
	v_rcp_f32_e32 v144, v225
	s_nop 0
	v_fma_f32 v222, -v220, v221, 1.0
	v_fma_f32 v146, -v225, v144, 1.0
	v_fmac_f32_e32 v221, v222, v221
	v_fmac_f32_e32 v144, v146, v144
	v_div_scale_f32 v222, vcc, v134, v138, v134
	v_mul_f32_e32 v223, v222, v221
	v_fma_f32 v224, -v220, v223, v222
	v_fmac_f32_e32 v223, v224, v221
	v_fma_f32 v222, -v220, v223, v222
	s_nop 0
	v_div_fmas_f32 v222, v222, v221, v223
	v_div_scale_f32 v146, vcc, v135, v139, v135
	v_mul_f32_e32 v141, v146, v144
	v_fma_f32 v143, -v225, v141, v146
	v_fmac_f32_e32 v141, v143, v144
	v_fma_f32 v146, -v225, v141, v146
	v_div_fixup_f32 v134, v222, v138, v134
	v_div_fmas_f32 v146, v146, v144, v141
	s_nop 0
	v_div_fixup_f32 v135, v146, v139, v135
	v_pk_mul_f32 v[136:137], v[134:135], v[136:137]
	s_nop 0
	v_cvt_pk_bf16_f32 v118, v136, v137
	v_lshlrev_b32_e32 v132, 16, v90
	v_and_b32_e32 v133, 0xffff0000, v90
	v_lshlrev_b32_e32 v134, 16, v122
	v_and_b32_e32 v135, 0xffff0000, v122
	v_mul_f32_e32 v138, 0xbfb8aa3b, v134
	v_mul_f32_e32 v139, 0xbfb8aa3b, v135
	v_exp_f32_e32 v138, v138
	v_exp_f32_e32 v139, v139
	v_pk_fma_f32 v[136:137], v[218:219], v[166:167], v[132:133] op_sel_hi:[1,0,1] neg_lo:[0,0,1] neg_hi:[0,0,1]
	v_add_f32_e32 v138, 1.0, v138
	v_add_f32_e32 v139, 1.0, v139
	v_pk_mul_f32 v[136:137], v[128:129], v[136:137]
	v_div_scale_f32 v220, s[4:5], v138, v138, v134
	v_div_scale_f32 v225, s[4:5], v139, v139, v135
	v_rcp_f32_e32 v221, v220
	v_rcp_f32_e32 v144, v225
	s_nop 0
	v_fma_f32 v222, -v220, v221, 1.0
	v_fma_f32 v146, -v225, v144, 1.0
	v_fmac_f32_e32 v221, v222, v221
	v_fmac_f32_e32 v144, v146, v144
	v_div_scale_f32 v222, vcc, v134, v138, v134
	v_mul_f32_e32 v223, v222, v221
	v_fma_f32 v224, -v220, v223, v222
	v_fmac_f32_e32 v223, v224, v221
	v_fma_f32 v222, -v220, v223, v222
	s_nop 0
	v_div_fmas_f32 v222, v222, v221, v223
	v_div_scale_f32 v146, vcc, v135, v139, v135
	v_mul_f32_e32 v141, v146, v144
	v_fma_f32 v143, -v225, v141, v146
	v_fmac_f32_e32 v141, v143, v144
	v_fma_f32 v146, -v225, v141, v146
	v_div_fixup_f32 v134, v222, v138, v134
	v_div_fmas_f32 v146, v146, v144, v141
	s_nop 0
	v_div_fixup_f32 v135, v146, v139, v135
	v_pk_mul_f32 v[136:137], v[134:135], v[136:137]
	s_nop 0
	v_cvt_pk_bf16_f32 v122, v136, v137
	v_lshlrev_b32_e32 v174, 16, v3
	v_and_b32_e32 v175, 0xffff0000, v3
	v_lshlrev_b32_e32 v176, 16, v7
	v_and_b32_e32 v177, 0xffff0000, v7
	v_lshlrev_b32_e32 v178, 16, v11
	v_and_b32_e32 v179, 0xffff0000, v11
	v_lshlrev_b32_e32 v180, 16, v15
	v_and_b32_e32 v181, 0xffff0000, v15
	v_lshlrev_b32_e32 v182, 16, v19
	v_and_b32_e32 v183, 0xffff0000, v19
	v_lshlrev_b32_e32 v184, 16, v23
	v_and_b32_e32 v185, 0xffff0000, v23
	v_lshlrev_b32_e32 v186, 16, v27
	v_and_b32_e32 v187, 0xffff0000, v27
	v_lshlrev_b32_e32 v188, 16, v31
	v_and_b32_e32 v189, 0xffff0000, v31
	v_lshlrev_b32_e32 v190, 16, v35
	v_and_b32_e32 v191, 0xffff0000, v35
	v_lshlrev_b32_e32 v192, 16, v39
	v_and_b32_e32 v193, 0xffff0000, v39
	v_lshlrev_b32_e32 v194, 16, v43
	v_and_b32_e32 v195, 0xffff0000, v43
	v_lshlrev_b32_e32 v196, 16, v47
	v_and_b32_e32 v197, 0xffff0000, v47
	v_lshlrev_b32_e32 v198, 16, v51
	v_and_b32_e32 v199, 0xffff0000, v51
	v_lshlrev_b32_e32 v200, 16, v55
	v_and_b32_e32 v201, 0xffff0000, v55
	v_lshlrev_b32_e32 v202, 16, v59
	v_and_b32_e32 v203, 0xffff0000, v59
	v_lshlrev_b32_e32 v204, 16, v63
	v_and_b32_e32 v205, 0xffff0000, v63
	v_lshlrev_b32_e32 v206, 16, v67
	v_and_b32_e32 v207, 0xffff0000, v67
	v_lshlrev_b32_e32 v208, 16, v71
	v_and_b32_e32 v209, 0xffff0000, v71
	v_lshlrev_b32_e32 v210, 16, v75
	v_and_b32_e32 v211, 0xffff0000, v75
	v_lshlrev_b32_e32 v212, 16, v79
	v_and_b32_e32 v213, 0xffff0000, v79
	v_lshlrev_b32_e32 v214, 16, v83
	v_and_b32_e32 v215, 0xffff0000, v83
	v_lshlrev_b32_e32 v216, 16, v87
	v_and_b32_e32 v217, 0xffff0000, v87
	v_lshlrev_b32_e32 v218, 16, v91
	v_and_b32_e32 v219, 0xffff0000, v91
	v_pk_add_f32 v[218:219], v[218:219], v[216:217]
	v_pk_add_f32 v[216:217], v[216:217], v[214:215]
	v_pk_add_f32 v[214:215], v[214:215], v[212:213]
	v_pk_add_f32 v[212:213], v[212:213], v[210:211]
	v_pk_add_f32 v[210:211], v[210:211], v[208:209]
	v_pk_add_f32 v[208:209], v[208:209], v[206:207]
	v_pk_add_f32 v[206:207], v[206:207], v[204:205]
	v_pk_add_f32 v[204:205], v[204:205], v[202:203]
	v_pk_add_f32 v[202:203], v[202:203], v[200:201]
	v_pk_add_f32 v[200:201], v[200:201], v[198:199]
	v_pk_add_f32 v[198:199], v[198:199], v[196:197]
	v_pk_add_f32 v[196:197], v[196:197], v[194:195]
	v_pk_add_f32 v[194:195], v[194:195], v[192:193]
	v_pk_add_f32 v[192:193], v[192:193], v[190:191]
	v_pk_add_f32 v[190:191], v[190:191], v[188:189]
	v_pk_add_f32 v[188:189], v[188:189], v[186:187]
	v_pk_add_f32 v[186:187], v[186:187], v[184:185]
	v_pk_add_f32 v[184:185], v[184:185], v[182:183]
	v_pk_add_f32 v[182:183], v[182:183], v[180:181]
	v_pk_add_f32 v[180:181], v[180:181], v[178:179]
	v_pk_add_f32 v[178:179], v[178:179], v[176:177]
	v_pk_add_f32 v[176:177], v[176:177], v[174:175]
	v_pk_fma_f32 v[218:219], v[214:215], v[168:169], v[218:219] op_sel_hi:[1,0,1]
	v_pk_fma_f32 v[216:217], v[212:213], v[168:169], v[216:217] op_sel_hi:[1,0,1]
	v_pk_fma_f32 v[214:215], v[210:211], v[168:169], v[214:215] op_sel_hi:[1,0,1]
	v_pk_fma_f32 v[212:213], v[208:209], v[168:169], v[212:213] op_sel_hi:[1,0,1]
	v_pk_fma_f32 v[210:211], v[206:207], v[168:169], v[210:211] op_sel_hi:[1,0,1]
	v_pk_fma_f32 v[208:209], v[204:205], v[168:169], v[208:209] op_sel_hi:[1,0,1]
	v_pk_fma_f32 v[206:207], v[202:203], v[168:169], v[206:207] op_sel_hi:[1,0,1]
	v_pk_fma_f32 v[204:205], v[200:201], v[168:169], v[204:205] op_sel_hi:[1,0,1]
	v_pk_fma_f32 v[202:203], v[198:199], v[168:169], v[202:203] op_sel_hi:[1,0,1]
	v_pk_fma_f32 v[200:201], v[196:197], v[168:169], v[200:201] op_sel_hi:[1,0,1]
	v_pk_fma_f32 v[198:199], v[194:195], v[168:169], v[198:199] op_sel_hi:[1,0,1]
	v_pk_fma_f32 v[196:197], v[192:193], v[168:169], v[196:197] op_sel_hi:[1,0,1]
	v_pk_fma_f32 v[194:195], v[190:191], v[168:169], v[194:195] op_sel_hi:[1,0,1]
	v_pk_fma_f32 v[192:193], v[188:189], v[168:169], v[192:193] op_sel_hi:[1,0,1]
	v_pk_fma_f32 v[190:191], v[186:187], v[168:169], v[190:191] op_sel_hi:[1,0,1]
	v_pk_fma_f32 v[188:189], v[184:185], v[168:169], v[188:189] op_sel_hi:[1,0,1]
	v_pk_fma_f32 v[186:187], v[182:183], v[168:169], v[186:187] op_sel_hi:[1,0,1]
	v_pk_fma_f32 v[184:185], v[180:181], v[168:169], v[184:185] op_sel_hi:[1,0,1]
	v_pk_fma_f32 v[182:183], v[178:179], v[168:169], v[182:183] op_sel_hi:[1,0,1]
	v_pk_fma_f32 v[180:181], v[176:177], v[168:169], v[180:181] op_sel_hi:[1,0,1]
	v_pk_fma_f32 v[218:219], v[210:211], v[170:171], v[218:219] op_sel_hi:[1,0,1]
	v_pk_fma_f32 v[216:217], v[208:209], v[170:171], v[216:217] op_sel_hi:[1,0,1]
	v_pk_fma_f32 v[214:215], v[206:207], v[170:171], v[214:215] op_sel_hi:[1,0,1]
	v_pk_fma_f32 v[212:213], v[204:205], v[170:171], v[212:213] op_sel_hi:[1,0,1]
	v_pk_fma_f32 v[210:211], v[202:203], v[170:171], v[210:211] op_sel_hi:[1,0,1]
	v_pk_fma_f32 v[208:209], v[200:201], v[170:171], v[208:209] op_sel_hi:[1,0,1]
	v_pk_fma_f32 v[206:207], v[198:199], v[170:171], v[206:207] op_sel_hi:[1,0,1]
	v_pk_fma_f32 v[204:205], v[196:197], v[170:171], v[204:205] op_sel_hi:[1,0,1]
	v_pk_fma_f32 v[202:203], v[194:195], v[170:171], v[202:203] op_sel_hi:[1,0,1]
	v_pk_fma_f32 v[200:201], v[192:193], v[170:171], v[200:201] op_sel_hi:[1,0,1]
	v_pk_fma_f32 v[198:199], v[190:191], v[170:171], v[198:199] op_sel_hi:[1,0,1]
	v_pk_fma_f32 v[196:197], v[188:189], v[170:171], v[196:197] op_sel_hi:[1,0,1]
	v_pk_fma_f32 v[194:195], v[186:187], v[170:171], v[194:195] op_sel_hi:[1,0,1]
	v_pk_fma_f32 v[192:193], v[184:185], v[170:171], v[192:193] op_sel_hi:[1,0,1]
	v_pk_fma_f32 v[190:191], v[182:183], v[170:171], v[190:191] op_sel_hi:[1,0,1]
	v_pk_fma_f32 v[188:189], v[180:181], v[170:171], v[188:189] op_sel_hi:[1,0,1]
	v_pk_fma_f32 v[218:219], v[202:203], v[172:173], v[218:219] op_sel_hi:[1,0,1]
	v_pk_fma_f32 v[216:217], v[200:201], v[172:173], v[216:217] op_sel_hi:[1,0,1]
	v_pk_fma_f32 v[214:215], v[198:199], v[172:173], v[214:215] op_sel_hi:[1,0,1]
	v_pk_fma_f32 v[212:213], v[196:197], v[172:173], v[212:213] op_sel_hi:[1,0,1]
	v_pk_fma_f32 v[210:211], v[194:195], v[172:173], v[210:211] op_sel_hi:[1,0,1]
	v_pk_fma_f32 v[208:209], v[192:193], v[172:173], v[208:209] op_sel_hi:[1,0,1]
	v_pk_fma_f32 v[206:207], v[190:191], v[172:173], v[206:207] op_sel_hi:[1,0,1]
	v_pk_fma_f32 v[204:205], v[188:189], v[172:173], v[204:205] op_sel_hi:[1,0,1]
	v_lshlrev_b32_e32 v132, 16, v63
	v_and_b32_e32 v133, 0xffff0000, v63
	v_lshlrev_b32_e32 v134, 16, v95
	v_and_b32_e32 v135, 0xffff0000, v95
	v_mul_f32_e32 v138, 0xbfb8aa3b, v134
	v_mul_f32_e32 v139, 0xbfb8aa3b, v135
	v_exp_f32_e32 v138, v138
	v_exp_f32_e32 v139, v139
	v_pk_fma_f32 v[136:137], v[204:205], v[152:153], v[132:133] op_sel_hi:[1,0,1] neg_lo:[0,0,1] neg_hi:[0,0,1]
	v_add_f32_e32 v138, 1.0, v138
	v_add_f32_e32 v139, 1.0, v139
	v_pk_mul_f32 v[136:137], v[130:131], v[136:137]
	v_div_scale_f32 v220, s[4:5], v138, v138, v134
	v_div_scale_f32 v225, s[4:5], v139, v139, v135
	v_rcp_f32_e32 v221, v220
	v_rcp_f32_e32 v144, v225
	s_nop 0
	v_fma_f32 v222, -v220, v221, 1.0
	v_fma_f32 v146, -v225, v144, 1.0
	v_fmac_f32_e32 v221, v222, v221
	v_fmac_f32_e32 v144, v146, v144
	v_div_scale_f32 v222, vcc, v134, v138, v134
	v_mul_f32_e32 v223, v222, v221
	v_fma_f32 v224, -v220, v223, v222
	v_fmac_f32_e32 v223, v224, v221
	v_fma_f32 v222, -v220, v223, v222
	s_nop 0
	v_div_fmas_f32 v222, v222, v221, v223
	v_div_scale_f32 v146, vcc, v135, v139, v135
	v_mul_f32_e32 v141, v146, v144
	v_fma_f32 v143, -v225, v141, v146
	v_fmac_f32_e32 v141, v143, v144
	v_fma_f32 v146, -v225, v141, v146
	v_div_fixup_f32 v134, v222, v138, v134
	v_div_fmas_f32 v146, v146, v144, v141
	s_nop 0
	v_div_fixup_f32 v135, v146, v139, v135
	v_pk_mul_f32 v[136:137], v[134:135], v[136:137]
	s_nop 0
	v_cvt_pk_bf16_f32 v95, v136, v137
	v_lshlrev_b32_e32 v132, 16, v67
	v_and_b32_e32 v133, 0xffff0000, v67
	v_lshlrev_b32_e32 v134, 16, v99
	v_and_b32_e32 v135, 0xffff0000, v99
	v_mul_f32_e32 v138, 0xbfb8aa3b, v134
	v_mul_f32_e32 v139, 0xbfb8aa3b, v135
	v_exp_f32_e32 v138, v138
	v_exp_f32_e32 v139, v139
	v_pk_fma_f32 v[136:137], v[206:207], v[154:155], v[132:133] op_sel_hi:[1,0,1] neg_lo:[0,0,1] neg_hi:[0,0,1]
	v_add_f32_e32 v138, 1.0, v138
	v_add_f32_e32 v139, 1.0, v139
	v_pk_mul_f32 v[136:137], v[130:131], v[136:137]
	v_div_scale_f32 v220, s[4:5], v138, v138, v134
	v_div_scale_f32 v225, s[4:5], v139, v139, v135
	v_rcp_f32_e32 v221, v220
	v_rcp_f32_e32 v144, v225
	s_nop 0
	v_fma_f32 v222, -v220, v221, 1.0
	v_fma_f32 v146, -v225, v144, 1.0
	v_fmac_f32_e32 v221, v222, v221
	v_fmac_f32_e32 v144, v146, v144
	v_div_scale_f32 v222, vcc, v134, v138, v134
	v_mul_f32_e32 v223, v222, v221
	v_fma_f32 v224, -v220, v223, v222
	v_fmac_f32_e32 v223, v224, v221
	v_fma_f32 v222, -v220, v223, v222
	s_nop 0
	v_div_fmas_f32 v222, v222, v221, v223
	v_div_scale_f32 v146, vcc, v135, v139, v135
	v_mul_f32_e32 v141, v146, v144
	v_fma_f32 v143, -v225, v141, v146
	v_fmac_f32_e32 v141, v143, v144
	v_fma_f32 v146, -v225, v141, v146
	v_div_fixup_f32 v134, v222, v138, v134
	v_div_fmas_f32 v146, v146, v144, v141
	s_nop 0
	v_div_fixup_f32 v135, v146, v139, v135
	v_pk_mul_f32 v[136:137], v[134:135], v[136:137]
	s_nop 0
	v_cvt_pk_bf16_f32 v99, v136, v137
	v_lshlrev_b32_e32 v132, 16, v71
	v_and_b32_e32 v133, 0xffff0000, v71
	v_lshlrev_b32_e32 v134, 16, v103
	v_and_b32_e32 v135, 0xffff0000, v103
	v_mul_f32_e32 v138, 0xbfb8aa3b, v134
	v_mul_f32_e32 v139, 0xbfb8aa3b, v135
	v_exp_f32_e32 v138, v138
	v_exp_f32_e32 v139, v139
	v_pk_fma_f32 v[136:137], v[208:209], v[156:157], v[132:133] op_sel_hi:[1,0,1] neg_lo:[0,0,1] neg_hi:[0,0,1]
	v_add_f32_e32 v138, 1.0, v138
	v_add_f32_e32 v139, 1.0, v139
	v_pk_mul_f32 v[136:137], v[130:131], v[136:137]
	v_div_scale_f32 v220, s[4:5], v138, v138, v134
	v_div_scale_f32 v225, s[4:5], v139, v139, v135
	v_rcp_f32_e32 v221, v220
	v_rcp_f32_e32 v144, v225
	s_nop 0
	v_fma_f32 v222, -v220, v221, 1.0
	v_fma_f32 v146, -v225, v144, 1.0
	v_fmac_f32_e32 v221, v222, v221
	v_fmac_f32_e32 v144, v146, v144
	v_div_scale_f32 v222, vcc, v134, v138, v134
	v_mul_f32_e32 v223, v222, v221
	v_fma_f32 v224, -v220, v223, v222
	v_fmac_f32_e32 v223, v224, v221
	v_fma_f32 v222, -v220, v223, v222
	s_nop 0
	v_div_fmas_f32 v222, v222, v221, v223
	v_div_scale_f32 v146, vcc, v135, v139, v135
	v_mul_f32_e32 v141, v146, v144
	v_fma_f32 v143, -v225, v141, v146
	v_fmac_f32_e32 v141, v143, v144
	v_fma_f32 v146, -v225, v141, v146
	v_div_fixup_f32 v134, v222, v138, v134
	v_div_fmas_f32 v146, v146, v144, v141
	s_nop 0
	v_div_fixup_f32 v135, v146, v139, v135
	v_pk_mul_f32 v[136:137], v[134:135], v[136:137]
	s_nop 0
	v_cvt_pk_bf16_f32 v103, v136, v137
	v_lshlrev_b32_e32 v132, 16, v75
	v_and_b32_e32 v133, 0xffff0000, v75
	v_lshlrev_b32_e32 v134, 16, v107
	v_and_b32_e32 v135, 0xffff0000, v107
	v_mul_f32_e32 v138, 0xbfb8aa3b, v134
	v_mul_f32_e32 v139, 0xbfb8aa3b, v135
	v_exp_f32_e32 v138, v138
	v_exp_f32_e32 v139, v139
	v_pk_fma_f32 v[136:137], v[210:211], v[158:159], v[132:133] op_sel_hi:[1,0,1] neg_lo:[0,0,1] neg_hi:[0,0,1]
	v_add_f32_e32 v138, 1.0, v138
	v_add_f32_e32 v139, 1.0, v139
	v_pk_mul_f32 v[136:137], v[130:131], v[136:137]
	v_div_scale_f32 v220, s[4:5], v138, v138, v134
	v_div_scale_f32 v225, s[4:5], v139, v139, v135
	v_rcp_f32_e32 v221, v220
	v_rcp_f32_e32 v144, v225
	s_nop 0
	v_fma_f32 v222, -v220, v221, 1.0
	v_fma_f32 v146, -v225, v144, 1.0
	v_fmac_f32_e32 v221, v222, v221
	v_fmac_f32_e32 v144, v146, v144
	v_div_scale_f32 v222, vcc, v134, v138, v134
	v_mul_f32_e32 v223, v222, v221
	v_fma_f32 v224, -v220, v223, v222
	v_fmac_f32_e32 v223, v224, v221
	v_fma_f32 v222, -v220, v223, v222
	s_nop 0
	v_div_fmas_f32 v222, v222, v221, v223
	v_div_scale_f32 v146, vcc, v135, v139, v135
	v_mul_f32_e32 v141, v146, v144
	v_fma_f32 v143, -v225, v141, v146
	v_fmac_f32_e32 v141, v143, v144
	v_fma_f32 v146, -v225, v141, v146
	v_div_fixup_f32 v134, v222, v138, v134
	v_div_fmas_f32 v146, v146, v144, v141
	s_nop 0
	v_div_fixup_f32 v135, v146, v139, v135
	v_pk_mul_f32 v[136:137], v[134:135], v[136:137]
	s_nop 0
	v_cvt_pk_bf16_f32 v107, v136, v137
	v_lshlrev_b32_e32 v132, 16, v79
	v_and_b32_e32 v133, 0xffff0000, v79
	v_lshlrev_b32_e32 v134, 16, v111
	v_and_b32_e32 v135, 0xffff0000, v111
	v_mul_f32_e32 v138, 0xbfb8aa3b, v134
	v_mul_f32_e32 v139, 0xbfb8aa3b, v135
	v_exp_f32_e32 v138, v138
	v_exp_f32_e32 v139, v139
	v_pk_fma_f32 v[136:137], v[212:213], v[160:161], v[132:133] op_sel_hi:[1,0,1] neg_lo:[0,0,1] neg_hi:[0,0,1]
	v_add_f32_e32 v138, 1.0, v138
	v_add_f32_e32 v139, 1.0, v139
	v_pk_mul_f32 v[136:137], v[130:131], v[136:137]
	v_div_scale_f32 v220, s[4:5], v138, v138, v134
	v_div_scale_f32 v225, s[4:5], v139, v139, v135
	v_rcp_f32_e32 v221, v220
	v_rcp_f32_e32 v144, v225
	s_nop 0
	v_fma_f32 v222, -v220, v221, 1.0
	v_fma_f32 v146, -v225, v144, 1.0
	v_fmac_f32_e32 v221, v222, v221
	v_fmac_f32_e32 v144, v146, v144
	v_div_scale_f32 v222, vcc, v134, v138, v134
	v_mul_f32_e32 v223, v222, v221
	v_fma_f32 v224, -v220, v223, v222
	v_fmac_f32_e32 v223, v224, v221
	v_fma_f32 v222, -v220, v223, v222
	s_nop 0
	v_div_fmas_f32 v222, v222, v221, v223
	v_div_scale_f32 v146, vcc, v135, v139, v135
	v_mul_f32_e32 v141, v146, v144
	v_fma_f32 v143, -v225, v141, v146
	v_fmac_f32_e32 v141, v143, v144
	v_fma_f32 v146, -v225, v141, v146
	v_div_fixup_f32 v134, v222, v138, v134
	v_div_fmas_f32 v146, v146, v144, v141
	s_nop 0
	v_div_fixup_f32 v135, v146, v139, v135
	v_pk_mul_f32 v[136:137], v[134:135], v[136:137]
	s_nop 0
	v_cvt_pk_bf16_f32 v111, v136, v137
	v_lshlrev_b32_e32 v132, 16, v83
	v_and_b32_e32 v133, 0xffff0000, v83
	v_lshlrev_b32_e32 v134, 16, v115
	v_and_b32_e32 v135, 0xffff0000, v115
	v_mul_f32_e32 v138, 0xbfb8aa3b, v134
	v_mul_f32_e32 v139, 0xbfb8aa3b, v135
	v_exp_f32_e32 v138, v138
	v_exp_f32_e32 v139, v139
	v_pk_fma_f32 v[136:137], v[214:215], v[162:163], v[132:133] op_sel_hi:[1,0,1] neg_lo:[0,0,1] neg_hi:[0,0,1]
	v_add_f32_e32 v138, 1.0, v138
	v_add_f32_e32 v139, 1.0, v139
	v_pk_mul_f32 v[136:137], v[130:131], v[136:137]
	v_div_scale_f32 v220, s[4:5], v138, v138, v134
	v_div_scale_f32 v225, s[4:5], v139, v139, v135
	v_rcp_f32_e32 v221, v220
	v_rcp_f32_e32 v144, v225
	s_nop 0
	v_fma_f32 v222, -v220, v221, 1.0
	v_fma_f32 v146, -v225, v144, 1.0
	v_fmac_f32_e32 v221, v222, v221
	v_fmac_f32_e32 v144, v146, v144
	v_div_scale_f32 v222, vcc, v134, v138, v134
	v_mul_f32_e32 v223, v222, v221
	v_fma_f32 v224, -v220, v223, v222
	v_fmac_f32_e32 v223, v224, v221
	v_fma_f32 v222, -v220, v223, v222
	s_nop 0
	v_div_fmas_f32 v222, v222, v221, v223
	v_div_scale_f32 v146, vcc, v135, v139, v135
	v_mul_f32_e32 v141, v146, v144
	v_fma_f32 v143, -v225, v141, v146
	v_fmac_f32_e32 v141, v143, v144
	v_fma_f32 v146, -v225, v141, v146
	v_div_fixup_f32 v134, v222, v138, v134
	v_div_fmas_f32 v146, v146, v144, v141
	s_nop 0
	v_div_fixup_f32 v135, v146, v139, v135
	v_pk_mul_f32 v[136:137], v[134:135], v[136:137]
	s_nop 0
	v_cvt_pk_bf16_f32 v115, v136, v137
	v_lshlrev_b32_e32 v132, 16, v87
	v_and_b32_e32 v133, 0xffff0000, v87
	v_lshlrev_b32_e32 v134, 16, v119
	v_and_b32_e32 v135, 0xffff0000, v119
	v_mul_f32_e32 v138, 0xbfb8aa3b, v134
	v_mul_f32_e32 v139, 0xbfb8aa3b, v135
	v_exp_f32_e32 v138, v138
	v_exp_f32_e32 v139, v139
	v_pk_fma_f32 v[136:137], v[216:217], v[164:165], v[132:133] op_sel_hi:[1,0,1] neg_lo:[0,0,1] neg_hi:[0,0,1]
	v_add_f32_e32 v138, 1.0, v138
	v_add_f32_e32 v139, 1.0, v139
	v_pk_mul_f32 v[136:137], v[130:131], v[136:137]
	v_div_scale_f32 v220, s[4:5], v138, v138, v134
	v_div_scale_f32 v225, s[4:5], v139, v139, v135
	v_rcp_f32_e32 v221, v220
	v_rcp_f32_e32 v144, v225
	s_nop 0
	v_fma_f32 v222, -v220, v221, 1.0
	v_fma_f32 v146, -v225, v144, 1.0
	v_fmac_f32_e32 v221, v222, v221
	v_fmac_f32_e32 v144, v146, v144
	v_div_scale_f32 v222, vcc, v134, v138, v134
	v_mul_f32_e32 v223, v222, v221
	v_fma_f32 v224, -v220, v223, v222
	v_fmac_f32_e32 v223, v224, v221
	v_fma_f32 v222, -v220, v223, v222
	s_nop 0
	v_div_fmas_f32 v222, v222, v221, v223
	v_div_scale_f32 v146, vcc, v135, v139, v135
	v_mul_f32_e32 v141, v146, v144
	v_fma_f32 v143, -v225, v141, v146
	v_fmac_f32_e32 v141, v143, v144
	v_fma_f32 v146, -v225, v141, v146
	v_div_fixup_f32 v134, v222, v138, v134
	v_div_fmas_f32 v146, v146, v144, v141
	s_nop 0
	v_div_fixup_f32 v135, v146, v139, v135
	v_pk_mul_f32 v[136:137], v[134:135], v[136:137]
	s_nop 0
	v_cvt_pk_bf16_f32 v119, v136, v137
	v_lshlrev_b32_e32 v132, 16, v91
	v_and_b32_e32 v133, 0xffff0000, v91
	v_lshlrev_b32_e32 v134, 16, v123
	v_and_b32_e32 v135, 0xffff0000, v123
	v_mul_f32_e32 v138, 0xbfb8aa3b, v134
	v_mul_f32_e32 v139, 0xbfb8aa3b, v135
	v_exp_f32_e32 v138, v138
	v_exp_f32_e32 v139, v139
	v_pk_fma_f32 v[136:137], v[218:219], v[166:167], v[132:133] op_sel_hi:[1,0,1] neg_lo:[0,0,1] neg_hi:[0,0,1]
	v_add_f32_e32 v138, 1.0, v138
	v_add_f32_e32 v139, 1.0, v139
	v_pk_mul_f32 v[136:137], v[130:131], v[136:137]
	v_div_scale_f32 v220, s[4:5], v138, v138, v134
	v_div_scale_f32 v225, s[4:5], v139, v139, v135
	v_rcp_f32_e32 v221, v220
	v_rcp_f32_e32 v144, v225
	s_nop 0
	v_fma_f32 v222, -v220, v221, 1.0
	v_fma_f32 v146, -v225, v144, 1.0
	v_fmac_f32_e32 v221, v222, v221
	v_fmac_f32_e32 v144, v146, v144
	v_div_scale_f32 v222, vcc, v134, v138, v134
	v_mul_f32_e32 v223, v222, v221
	v_fma_f32 v224, -v220, v223, v222
	v_fmac_f32_e32 v223, v224, v221
	v_fma_f32 v222, -v220, v223, v222
	s_nop 0
	v_div_fmas_f32 v222, v222, v221, v223
	v_div_scale_f32 v146, vcc, v135, v139, v135
	v_mul_f32_e32 v141, v146, v144
	v_fma_f32 v143, -v225, v141, v146
	v_fmac_f32_e32 v141, v143, v144
	v_fma_f32 v146, -v225, v141, v146
	v_div_fixup_f32 v134, v222, v138, v134
	v_div_fmas_f32 v146, v146, v144, v141
	s_nop 0
	v_div_fixup_f32 v135, v146, v139, v135
	v_pk_mul_f32 v[136:137], v[134:135], v[136:137]
	s_nop 0
	v_cvt_pk_bf16_f32 v123, v136, v137
	s_add_i32 s0, s6, 15
	s_lshl_b32 s0, s0, 10
	v_and_b32_e32 v143, 63, v226
	v_lshlrev_b32_e32 v142, 4, v143
	v_add_u32_e32 v142, s0, v142
	global_store_dwordx4 v142, v[92:95], s[44:45]
	v_add_u32_e32 v142, 0x400, v142
	global_store_dwordx4 v142, v[96:99], s[44:45]
	v_add_u32_e32 v142, 0x400, v142
	global_store_dwordx4 v142, v[100:103], s[44:45]
	v_add_u32_e32 v142, 0x400, v142
	global_store_dwordx4 v142, v[104:107], s[44:45]
	v_add_u32_e32 v142, 0x400, v142
	global_store_dwordx4 v142, v[108:111], s[44:45]
	v_add_u32_e32 v142, 0x400, v142
	global_store_dwordx4 v142, v[112:115], s[44:45]
	v_add_u32_e32 v142, 0x400, v142
	global_store_dwordx4 v142, v[116:119], s[44:45]
	v_add_u32_e32 v142, 0x400, v142
	global_store_dwordx4 v142, v[120:123], s[44:45]
	v_readlane_b32 s0, v254, 49
	s_add_i32 s55, s55, s40
	s_add_i32 s54, s54, s0
	s_cmpk_gt_i32 s55, 0xff
	s_cbranch_scc0 .LBB0_298
